# xattn softmax row max: the xor-32 ds_bpermute round trip replaced by copy + v_permlane32_swap (one LDS latency off the unit's serial chain)
# speedup vs baseline: 1.0029x; 1.0009x over previous
.LBB0_760:
	v_add_u32_e32 v181, 0x11800, v211
	v_add_u32_e32 v220, 0x15e00, v211
	v_add_u32_e32 v221, 0x1a400, v211
	v_add_u32_e32 v222, 0x1ea00, v211
	global_load_dwordx4 v[212:215], v[170:171], off offset:-128
	global_load_dwordx4 v[216:219], v[170:171], off offset:-96
	global_load_dwordx4 v[248:251], v[170:171], off offset:-64
	ds_read_b128 v[224:227], v211
	ds_read_b128 v[228:231], v211 offset:17920
	ds_read_b128 v[232:235], v211 offset:35840
	ds_read_b128 v[236:239], v211 offset:53760
	ds_read_b128 v[240:243], v181
	ds_read_b128 v[244:247], v220
	s_waitcnt vmcnt(2) lgkmcnt(5)
	v_mfma_f32_32x32x16_bf16 v[112:127], v[224:227], v[212:215], 0
	ds_read_b128 v[224:227], v221
	s_waitcnt lgkmcnt(5)
	v_mfma_f32_32x32x16_bf16 v[96:111], v[228:231], v[212:215], 0
	ds_read_b128 v[228:231], v222
	s_waitcnt lgkmcnt(5)
	v_mfma_f32_32x32x16_bf16 v[80:95], v[232:235], v[212:215], 0
	ds_read_b128 v[232:235], v211 offset:32
	s_waitcnt lgkmcnt(5)
	v_mfma_f32_32x32x16_bf16 v[64:79], v[236:239], v[212:215], 0
	ds_read_b128 v[236:239], v211 offset:17952
	s_waitcnt lgkmcnt(5)
	v_mfma_f32_32x32x16_bf16 v[48:63], v[240:243], v[212:215], 0
	ds_read_b128 v[240:243], v211 offset:35872
	s_waitcnt lgkmcnt(5)
	v_mfma_f32_32x32x16_bf16 v[32:47], v[244:247], v[212:215], 0
	ds_read_b128 v[244:247], v211 offset:53792
	s_waitcnt lgkmcnt(5)
	v_mfma_f32_32x32x16_bf16 v[16:31], v[224:227], v[212:215], 0
	ds_read_b128 v[224:227], v181 offset:32
	s_waitcnt lgkmcnt(5)
	v_mfma_f32_32x32x16_bf16 v[0:15], v[228:231], v[212:215], 0
	ds_read_b128 v[228:231], v220 offset:32
	global_load_dwordx4 v[212:215], v[170:171], off offset:-32
	s_waitcnt vmcnt(2) lgkmcnt(5)
	v_mfma_f32_32x32x16_bf16 v[112:127], v[232:235], v[216:219], v[112:127]
	ds_read_b128 v[232:235], v221 offset:32
	s_waitcnt lgkmcnt(5)
	v_mfma_f32_32x32x16_bf16 v[96:111], v[236:239], v[216:219], v[96:111]
	ds_read_b128 v[236:239], v222 offset:32
	s_waitcnt lgkmcnt(5)
	v_mfma_f32_32x32x16_bf16 v[80:95], v[240:243], v[216:219], v[80:95]
	ds_read_b128 v[240:243], v211 offset:64
	s_waitcnt lgkmcnt(5)
	v_mfma_f32_32x32x16_bf16 v[64:79], v[244:247], v[216:219], v[64:79]
	ds_read_b128 v[244:247], v211 offset:17984
	s_waitcnt lgkmcnt(5)
	v_mfma_f32_32x32x16_bf16 v[48:63], v[224:227], v[216:219], v[48:63]
	ds_read_b128 v[224:227], v211 offset:35904
	s_waitcnt lgkmcnt(5)
	v_mfma_f32_32x32x16_bf16 v[32:47], v[228:231], v[216:219], v[32:47]
	ds_read_b128 v[228:231], v211 offset:53824
	s_waitcnt lgkmcnt(5)
	v_mfma_f32_32x32x16_bf16 v[16:31], v[232:235], v[216:219], v[16:31]
	ds_read_b128 v[232:235], v181 offset:64
	s_waitcnt lgkmcnt(5)
	v_mfma_f32_32x32x16_bf16 v[0:15], v[236:239], v[216:219], v[0:15]
	ds_read_b128 v[236:239], v220 offset:64
	global_load_dwordx4 v[216:219], v[170:171], off
	s_waitcnt vmcnt(2) lgkmcnt(5)
	v_mfma_f32_32x32x16_bf16 v[112:127], v[240:243], v[248:251], v[112:127]
	ds_read_b128 v[240:243], v221 offset:64
	s_waitcnt lgkmcnt(5)
	v_mfma_f32_32x32x16_bf16 v[96:111], v[244:247], v[248:251], v[96:111]
	ds_read_b128 v[244:247], v222 offset:64
	s_waitcnt lgkmcnt(5)
	v_mfma_f32_32x32x16_bf16 v[80:95], v[224:227], v[248:251], v[80:95]
	ds_read_b128 v[224:227], v211 offset:96
	s_waitcnt lgkmcnt(5)
	v_mfma_f32_32x32x16_bf16 v[64:79], v[228:231], v[248:251], v[64:79]
	ds_read_b128 v[228:231], v211 offset:18016
	s_waitcnt lgkmcnt(5)
	v_mfma_f32_32x32x16_bf16 v[48:63], v[232:235], v[248:251], v[48:63]
	ds_read_b128 v[232:235], v211 offset:35936
	s_waitcnt lgkmcnt(5)
	v_mfma_f32_32x32x16_bf16 v[32:47], v[236:239], v[248:251], v[32:47]
	ds_read_b128 v[236:239], v211 offset:53856
	s_waitcnt lgkmcnt(5)
	v_mfma_f32_32x32x16_bf16 v[16:31], v[240:243], v[248:251], v[16:31]
	ds_read_b128 v[240:243], v181 offset:96
	s_waitcnt lgkmcnt(5)
	v_mfma_f32_32x32x16_bf16 v[0:15], v[244:247], v[248:251], v[0:15]
	ds_read_b128 v[244:247], v220 offset:96
	global_load_dwordx4 v[248:251], v[170:171], off offset:32
	s_waitcnt vmcnt(2) lgkmcnt(5)
	v_mfma_f32_32x32x16_bf16 v[112:127], v[224:227], v[212:215], v[112:127]
	ds_read_b128 v[224:227], v221 offset:96
	s_waitcnt lgkmcnt(5)
	v_mfma_f32_32x32x16_bf16 v[96:111], v[228:231], v[212:215], v[96:111]
	ds_read_b128 v[228:231], v222 offset:96
	s_waitcnt lgkmcnt(5)
	v_mfma_f32_32x32x16_bf16 v[80:95], v[232:235], v[212:215], v[80:95]
	ds_read_b128 v[232:235], v211 offset:128
	s_waitcnt lgkmcnt(5)
	v_mfma_f32_32x32x16_bf16 v[64:79], v[236:239], v[212:215], v[64:79]
	ds_read_b128 v[236:239], v211 offset:18048
	s_waitcnt lgkmcnt(5)
	v_mfma_f32_32x32x16_bf16 v[48:63], v[240:243], v[212:215], v[48:63]
	ds_read_b128 v[240:243], v211 offset:35968
	s_waitcnt lgkmcnt(5)
	v_mfma_f32_32x32x16_bf16 v[32:47], v[244:247], v[212:215], v[32:47]
	ds_read_b128 v[244:247], v211 offset:53888
	s_waitcnt lgkmcnt(5)
	v_mfma_f32_32x32x16_bf16 v[16:31], v[224:227], v[212:215], v[16:31]
	ds_read_b128 v[224:227], v181 offset:128
	s_waitcnt lgkmcnt(5)
	v_mfma_f32_32x32x16_bf16 v[0:15], v[228:231], v[212:215], v[0:15]
	ds_read_b128 v[228:231], v220 offset:128
	global_load_dwordx4 v[212:215], v[170:171], off offset:64
	s_waitcnt vmcnt(2) lgkmcnt(5)
	v_mfma_f32_32x32x16_bf16 v[112:127], v[232:235], v[216:219], v[112:127]
	ds_read_b128 v[232:235], v221 offset:128
	s_waitcnt lgkmcnt(5)
	v_mfma_f32_32x32x16_bf16 v[96:111], v[236:239], v[216:219], v[96:111]
	ds_read_b128 v[236:239], v222 offset:128
	s_waitcnt lgkmcnt(5)
	v_mfma_f32_32x32x16_bf16 v[80:95], v[240:243], v[216:219], v[80:95]
	ds_read_b128 v[240:243], v211 offset:160
	s_waitcnt lgkmcnt(5)
	v_mfma_f32_32x32x16_bf16 v[64:79], v[244:247], v[216:219], v[64:79]
	ds_read_b128 v[244:247], v211 offset:18080
	s_waitcnt lgkmcnt(5)
	v_mfma_f32_32x32x16_bf16 v[48:63], v[224:227], v[216:219], v[48:63]
	ds_read_b128 v[224:227], v211 offset:36000
	s_waitcnt lgkmcnt(5)
	v_mfma_f32_32x32x16_bf16 v[32:47], v[228:231], v[216:219], v[32:47]
	ds_read_b128 v[228:231], v211 offset:53920
	s_waitcnt lgkmcnt(5)
	v_mfma_f32_32x32x16_bf16 v[16:31], v[232:235], v[216:219], v[16:31]
	ds_read_b128 v[232:235], v181 offset:160
	s_waitcnt lgkmcnt(5)
	v_mfma_f32_32x32x16_bf16 v[0:15], v[236:239], v[216:219], v[0:15]
	ds_read_b128 v[236:239], v220 offset:160
	global_load_dwordx4 v[216:219], v[170:171], off offset:96
	s_waitcnt vmcnt(2) lgkmcnt(5)
	v_mfma_f32_32x32x16_bf16 v[112:127], v[240:243], v[248:251], v[112:127]
	ds_read_b128 v[240:243], v221 offset:160
	s_waitcnt lgkmcnt(5)
	v_mfma_f32_32x32x16_bf16 v[96:111], v[244:247], v[248:251], v[96:111]
	ds_read_b128 v[244:247], v222 offset:160
	s_waitcnt lgkmcnt(5)
	v_mfma_f32_32x32x16_bf16 v[80:95], v[224:227], v[248:251], v[80:95]
	ds_read_b128 v[224:227], v211 offset:192
	s_waitcnt lgkmcnt(5)
	v_mfma_f32_32x32x16_bf16 v[64:79], v[228:231], v[248:251], v[64:79]
	ds_read_b128 v[228:231], v211 offset:18112
	s_waitcnt lgkmcnt(5)
	v_mfma_f32_32x32x16_bf16 v[48:63], v[232:235], v[248:251], v[48:63]
	ds_read_b128 v[232:235], v211 offset:36032
	s_waitcnt lgkmcnt(5)
	v_mfma_f32_32x32x16_bf16 v[32:47], v[236:239], v[248:251], v[32:47]
	ds_read_b128 v[236:239], v211 offset:53952
	s_waitcnt lgkmcnt(5)
	v_mfma_f32_32x32x16_bf16 v[16:31], v[240:243], v[248:251], v[16:31]
	ds_read_b128 v[240:243], v181 offset:192
	s_waitcnt lgkmcnt(5)
	v_mfma_f32_32x32x16_bf16 v[0:15], v[244:247], v[248:251], v[0:15]
	ds_read_b128 v[244:247], v220 offset:192
	global_load_dwordx4 v[248:251], v[170:171], off offset:128
	s_waitcnt vmcnt(2) lgkmcnt(5)
	v_mfma_f32_32x32x16_bf16 v[112:127], v[224:227], v[212:215], v[112:127]
	ds_read_b128 v[224:227], v221 offset:192
	s_waitcnt lgkmcnt(5)
	v_mfma_f32_32x32x16_bf16 v[96:111], v[228:231], v[212:215], v[96:111]
	ds_read_b128 v[228:231], v222 offset:192
	s_waitcnt lgkmcnt(5)
	v_mfma_f32_32x32x16_bf16 v[80:95], v[232:235], v[212:215], v[80:95]
	ds_read_b128 v[232:235], v211 offset:224
	s_waitcnt lgkmcnt(5)
	v_mfma_f32_32x32x16_bf16 v[64:79], v[236:239], v[212:215], v[64:79]
	ds_read_b128 v[236:239], v211 offset:18144
	s_waitcnt lgkmcnt(5)
	v_mfma_f32_32x32x16_bf16 v[48:63], v[240:243], v[212:215], v[48:63]
	ds_read_b128 v[240:243], v211 offset:36064
	s_waitcnt lgkmcnt(5)
	v_mfma_f32_32x32x16_bf16 v[32:47], v[244:247], v[212:215], v[32:47]
	ds_read_b128 v[244:247], v211 offset:53984
	s_waitcnt lgkmcnt(5)
	v_mfma_f32_32x32x16_bf16 v[16:31], v[224:227], v[212:215], v[16:31]
	ds_read_b128 v[224:227], v181 offset:224
	s_waitcnt lgkmcnt(5)
	v_mfma_f32_32x32x16_bf16 v[0:15], v[228:231], v[212:215], v[0:15]
	ds_read_b128 v[228:231], v220 offset:224
	global_load_dwordx4 v[212:215], v[170:171], off offset:160
	s_waitcnt vmcnt(2) lgkmcnt(5)
	v_mfma_f32_32x32x16_bf16 v[112:127], v[232:235], v[216:219], v[112:127]
	ds_read_b128 v[232:235], v221 offset:224
	s_waitcnt lgkmcnt(5)
	v_mfma_f32_32x32x16_bf16 v[96:111], v[236:239], v[216:219], v[96:111]
	ds_read_b128 v[236:239], v222 offset:224
	s_waitcnt lgkmcnt(5)
	v_mfma_f32_32x32x16_bf16 v[80:95], v[240:243], v[216:219], v[80:95]
	ds_read_b128 v[240:243], v211 offset:256
	s_waitcnt lgkmcnt(5)
	v_mfma_f32_32x32x16_bf16 v[64:79], v[244:247], v[216:219], v[64:79]
	ds_read_b128 v[244:247], v211 offset:18176
	s_waitcnt lgkmcnt(5)
	v_mfma_f32_32x32x16_bf16 v[48:63], v[224:227], v[216:219], v[48:63]
	ds_read_b128 v[224:227], v211 offset:36096
	s_waitcnt lgkmcnt(5)
	v_mfma_f32_32x32x16_bf16 v[32:47], v[228:231], v[216:219], v[32:47]
	ds_read_b128 v[228:231], v211 offset:54016
	s_waitcnt lgkmcnt(5)
	v_mfma_f32_32x32x16_bf16 v[16:31], v[232:235], v[216:219], v[16:31]
	ds_read_b128 v[232:235], v181 offset:256
	s_waitcnt lgkmcnt(5)
	v_mfma_f32_32x32x16_bf16 v[0:15], v[236:239], v[216:219], v[0:15]
	ds_read_b128 v[236:239], v220 offset:256
	global_load_dwordx4 v[216:219], v[170:171], off offset:192
	s_waitcnt vmcnt(2) lgkmcnt(5)
	v_mfma_f32_32x32x16_bf16 v[112:127], v[240:243], v[248:251], v[112:127]
	ds_read_b128 v[240:243], v221 offset:256
	s_waitcnt lgkmcnt(5)
	v_mfma_f32_32x32x16_bf16 v[96:111], v[244:247], v[248:251], v[96:111]
	ds_read_b128 v[244:247], v222 offset:256
	s_waitcnt lgkmcnt(5)
	v_mfma_f32_32x32x16_bf16 v[80:95], v[224:227], v[248:251], v[80:95]
	ds_read_b128 v[224:227], v211 offset:288
	s_waitcnt lgkmcnt(5)
	v_mfma_f32_32x32x16_bf16 v[64:79], v[228:231], v[248:251], v[64:79]
	ds_read_b128 v[228:231], v211 offset:18208
	s_waitcnt lgkmcnt(5)
	v_mfma_f32_32x32x16_bf16 v[48:63], v[232:235], v[248:251], v[48:63]
	ds_read_b128 v[232:235], v211 offset:36128
	s_waitcnt lgkmcnt(5)
	v_mfma_f32_32x32x16_bf16 v[32:47], v[236:239], v[248:251], v[32:47]
	ds_read_b128 v[236:239], v211 offset:54048
	s_waitcnt lgkmcnt(5)
	v_mfma_f32_32x32x16_bf16 v[16:31], v[240:243], v[248:251], v[16:31]
	ds_read_b128 v[240:243], v181 offset:288
	s_waitcnt lgkmcnt(5)
	v_mfma_f32_32x32x16_bf16 v[0:15], v[244:247], v[248:251], v[0:15]
	ds_read_b128 v[244:247], v220 offset:288
	global_load_dwordx4 v[248:251], v[170:171], off offset:224
	s_waitcnt vmcnt(2) lgkmcnt(5)
	v_mfma_f32_32x32x16_bf16 v[112:127], v[224:227], v[212:215], v[112:127]
	ds_read_b128 v[224:227], v221 offset:288
	s_waitcnt lgkmcnt(5)
	v_mfma_f32_32x32x16_bf16 v[96:111], v[228:231], v[212:215], v[96:111]
	ds_read_b128 v[228:231], v222 offset:288
	s_waitcnt lgkmcnt(5)
	v_mfma_f32_32x32x16_bf16 v[80:95], v[232:235], v[212:215], v[80:95]
	ds_read_b128 v[232:235], v211 offset:320
	s_waitcnt lgkmcnt(5)
	v_mfma_f32_32x32x16_bf16 v[64:79], v[236:239], v[212:215], v[64:79]
	ds_read_b128 v[236:239], v211 offset:18240
	s_waitcnt lgkmcnt(5)
	v_mfma_f32_32x32x16_bf16 v[48:63], v[240:243], v[212:215], v[48:63]
	ds_read_b128 v[240:243], v211 offset:36160
	s_waitcnt lgkmcnt(5)
	v_mfma_f32_32x32x16_bf16 v[32:47], v[244:247], v[212:215], v[32:47]
	ds_read_b128 v[244:247], v211 offset:54080
	s_waitcnt lgkmcnt(5)
	v_mfma_f32_32x32x16_bf16 v[16:31], v[224:227], v[212:215], v[16:31]
	ds_read_b128 v[224:227], v181 offset:320
	s_waitcnt lgkmcnt(5)
	v_mfma_f32_32x32x16_bf16 v[0:15], v[228:231], v[212:215], v[0:15]
	ds_read_b128 v[228:231], v220 offset:320
	global_load_dwordx4 v[212:215], v[170:171], off offset:256
	s_waitcnt vmcnt(2) lgkmcnt(5)
	v_mfma_f32_32x32x16_bf16 v[112:127], v[232:235], v[216:219], v[112:127]
	ds_read_b128 v[232:235], v221 offset:320
	s_waitcnt lgkmcnt(5)
	v_mfma_f32_32x32x16_bf16 v[96:111], v[236:239], v[216:219], v[96:111]
	ds_read_b128 v[236:239], v222 offset:320
	s_waitcnt lgkmcnt(5)
	v_mfma_f32_32x32x16_bf16 v[80:95], v[240:243], v[216:219], v[80:95]
	ds_read_b128 v[240:243], v211 offset:352
	s_waitcnt lgkmcnt(5)
	v_mfma_f32_32x32x16_bf16 v[64:79], v[244:247], v[216:219], v[64:79]
	ds_read_b128 v[244:247], v211 offset:18272
	s_waitcnt lgkmcnt(5)
	v_mfma_f32_32x32x16_bf16 v[48:63], v[224:227], v[216:219], v[48:63]
	ds_read_b128 v[224:227], v211 offset:36192
	s_waitcnt lgkmcnt(5)
	v_mfma_f32_32x32x16_bf16 v[32:47], v[228:231], v[216:219], v[32:47]
	ds_read_b128 v[228:231], v211 offset:54112
	s_waitcnt lgkmcnt(5)
	v_mfma_f32_32x32x16_bf16 v[16:31], v[232:235], v[216:219], v[16:31]
	ds_read_b128 v[232:235], v181 offset:352
	s_waitcnt lgkmcnt(5)
	v_mfma_f32_32x32x16_bf16 v[0:15], v[236:239], v[216:219], v[0:15]
	ds_read_b128 v[236:239], v220 offset:352
	global_load_dwordx4 v[216:219], v[170:171], off offset:288
	s_waitcnt vmcnt(2) lgkmcnt(5)
	v_mfma_f32_32x32x16_bf16 v[112:127], v[240:243], v[248:251], v[112:127]
	ds_read_b128 v[240:243], v221 offset:352
	s_waitcnt lgkmcnt(5)
	v_mfma_f32_32x32x16_bf16 v[96:111], v[244:247], v[248:251], v[96:111]
	ds_read_b128 v[244:247], v222 offset:352
	s_waitcnt lgkmcnt(5)
	v_mfma_f32_32x32x16_bf16 v[80:95], v[224:227], v[248:251], v[80:95]
	ds_read_b128 v[224:227], v211 offset:384
	s_waitcnt lgkmcnt(5)
	v_mfma_f32_32x32x16_bf16 v[64:79], v[228:231], v[248:251], v[64:79]
	ds_read_b128 v[228:231], v211 offset:18304
	s_waitcnt lgkmcnt(5)
	v_mfma_f32_32x32x16_bf16 v[48:63], v[232:235], v[248:251], v[48:63]
	ds_read_b128 v[232:235], v211 offset:36224
	s_waitcnt lgkmcnt(5)
	v_mfma_f32_32x32x16_bf16 v[32:47], v[236:239], v[248:251], v[32:47]
	ds_read_b128 v[236:239], v211 offset:54144
	s_waitcnt lgkmcnt(5)
	v_mfma_f32_32x32x16_bf16 v[16:31], v[240:243], v[248:251], v[16:31]
	ds_read_b128 v[240:243], v181 offset:384
	s_waitcnt lgkmcnt(5)
	v_mfma_f32_32x32x16_bf16 v[0:15], v[244:247], v[248:251], v[0:15]
	ds_read_b128 v[244:247], v220 offset:384
	global_load_dwordx4 v[248:251], v[170:171], off offset:320
	s_waitcnt vmcnt(2) lgkmcnt(5)
	v_mfma_f32_32x32x16_bf16 v[112:127], v[224:227], v[212:215], v[112:127]
	ds_read_b128 v[224:227], v221 offset:384
	s_waitcnt lgkmcnt(5)
	v_mfma_f32_32x32x16_bf16 v[96:111], v[228:231], v[212:215], v[96:111]
	ds_read_b128 v[228:231], v222 offset:384
	s_waitcnt lgkmcnt(5)
	v_mfma_f32_32x32x16_bf16 v[80:95], v[232:235], v[212:215], v[80:95]
	ds_read_b128 v[232:235], v211 offset:416
	s_waitcnt lgkmcnt(5)
	v_mfma_f32_32x32x16_bf16 v[64:79], v[236:239], v[212:215], v[64:79]
	ds_read_b128 v[236:239], v211 offset:18336
	s_waitcnt lgkmcnt(5)
	v_mfma_f32_32x32x16_bf16 v[48:63], v[240:243], v[212:215], v[48:63]
	ds_read_b128 v[240:243], v211 offset:36256
	s_waitcnt lgkmcnt(5)
	v_mfma_f32_32x32x16_bf16 v[32:47], v[244:247], v[212:215], v[32:47]
	ds_read_b128 v[244:247], v211 offset:54176
	s_waitcnt lgkmcnt(5)
	v_mfma_f32_32x32x16_bf16 v[16:31], v[224:227], v[212:215], v[16:31]
	ds_read_b128 v[224:227], v181 offset:416
	s_waitcnt lgkmcnt(5)
	v_mfma_f32_32x32x16_bf16 v[0:15], v[228:231], v[212:215], v[0:15]
	ds_read_b128 v[228:231], v220 offset:416
	global_load_dwordx4 v[212:215], v[170:171], off offset:352
	s_waitcnt vmcnt(2) lgkmcnt(5)
	v_mfma_f32_32x32x16_bf16 v[112:127], v[232:235], v[216:219], v[112:127]
	ds_read_b128 v[232:235], v221 offset:416
	s_waitcnt lgkmcnt(5)
	v_mfma_f32_32x32x16_bf16 v[96:111], v[236:239], v[216:219], v[96:111]
	ds_read_b128 v[236:239], v222 offset:416
	s_waitcnt lgkmcnt(5)
	v_mfma_f32_32x32x16_bf16 v[80:95], v[240:243], v[216:219], v[80:95]
	ds_read_b128 v[240:243], v211 offset:448
	s_waitcnt lgkmcnt(5)
	v_mfma_f32_32x32x16_bf16 v[64:79], v[244:247], v[216:219], v[64:79]
	ds_read_b128 v[244:247], v211 offset:18368
	s_waitcnt lgkmcnt(5)
	v_mfma_f32_32x32x16_bf16 v[48:63], v[224:227], v[216:219], v[48:63]
	ds_read_b128 v[224:227], v211 offset:36288
	s_waitcnt lgkmcnt(5)
	v_mfma_f32_32x32x16_bf16 v[32:47], v[228:231], v[216:219], v[32:47]
	ds_read_b128 v[228:231], v211 offset:54208
	s_waitcnt lgkmcnt(5)
	v_mfma_f32_32x32x16_bf16 v[16:31], v[232:235], v[216:219], v[16:31]
	ds_read_b128 v[232:235], v181 offset:448
	s_waitcnt lgkmcnt(5)
	v_mfma_f32_32x32x16_bf16 v[0:15], v[236:239], v[216:219], v[0:15]
	ds_read_b128 v[236:239], v220 offset:448
	s_waitcnt vmcnt(1) lgkmcnt(5)
	v_mfma_f32_32x32x16_bf16 v[112:127], v[240:243], v[248:251], v[112:127]
	ds_read_b128 v[240:243], v221 offset:448
	s_waitcnt lgkmcnt(5)
	v_mfma_f32_32x32x16_bf16 v[96:111], v[244:247], v[248:251], v[96:111]
	ds_read_b128 v[244:247], v222 offset:448
	s_waitcnt lgkmcnt(5)
	v_mfma_f32_32x32x16_bf16 v[80:95], v[224:227], v[248:251], v[80:95]
	ds_read_b128 v[224:227], v211 offset:480
	s_waitcnt lgkmcnt(5)
	v_mfma_f32_32x32x16_bf16 v[64:79], v[228:231], v[248:251], v[64:79]
	ds_read_b128 v[228:231], v211 offset:18400
	s_waitcnt lgkmcnt(5)
	v_mfma_f32_32x32x16_bf16 v[48:63], v[232:235], v[248:251], v[48:63]
	ds_read_b128 v[232:235], v211 offset:36320
	s_waitcnt lgkmcnt(5)
	v_mfma_f32_32x32x16_bf16 v[32:47], v[236:239], v[248:251], v[32:47]
	ds_read_b128 v[236:239], v211 offset:54240
	s_waitcnt lgkmcnt(5)
	v_mfma_f32_32x32x16_bf16 v[16:31], v[240:243], v[248:251], v[16:31]
	ds_read_b128 v[240:243], v181 offset:480
	s_waitcnt lgkmcnt(5)
	v_mfma_f32_32x32x16_bf16 v[0:15], v[244:247], v[248:251], v[0:15]
	ds_read_b128 v[244:247], v220 offset:480
	s_waitcnt vmcnt(0) lgkmcnt(5)
	v_mfma_f32_32x32x16_bf16 v[112:127], v[224:227], v[212:215], v[112:127]
	ds_read_b128 v[224:227], v221 offset:480
	s_waitcnt lgkmcnt(5)
	v_mfma_f32_32x32x16_bf16 v[96:111], v[228:231], v[212:215], v[96:111]
	ds_read_b128 v[228:231], v222 offset:480
	s_waitcnt lgkmcnt(5)
	v_mfma_f32_32x32x16_bf16 v[80:95], v[232:235], v[212:215], v[80:95]
	s_waitcnt lgkmcnt(4)
	v_mfma_f32_32x32x16_bf16 v[64:79], v[236:239], v[212:215], v[64:79]
	s_waitcnt lgkmcnt(3)
	v_mfma_f32_32x32x16_bf16 v[48:63], v[240:243], v[212:215], v[48:63]
	s_waitcnt lgkmcnt(2)
	v_mfma_f32_32x32x16_bf16 v[32:47], v[244:247], v[212:215], v[32:47]
	s_waitcnt lgkmcnt(1)
	v_mfma_f32_32x32x16_bf16 v[16:31], v[224:227], v[212:215], v[16:31]
	s_waitcnt lgkmcnt(0)
	v_mfma_f32_32x32x16_bf16 v[0:15], v[228:231], v[212:215], v[0:15]
	s_movk_i32 s47, 0x200
	v_lshl_add_u64 v[244:245], v[160:161], 0, s[38:39]
	global_load_dwordx4 v[212:215], v[160:161], off offset:2432
	global_load_dwordx4 v[216:219], v[160:161], off offset:2304
	global_load_dwordx4 v[224:227], v[160:161], off offset:2176
	global_load_dwordx4 v[228:231], v[160:161], off offset:2048
	global_load_dwordx4 v[232:235], v[168:169], off offset:2048
	global_load_dwordx4 v[236:239], v[244:245], off offset:384
	global_load_dwordx4 v[240:243], v[244:245], off offset:256
	global_load_dwordx4 v[246:249], v[244:245], off offset:128
	v_mov_b32_e32 v170, v145
	v_mov_b32_e32 v171, v146
	v_mov_b32_e32 v145, v147
	v_mov_b32_e32 v146, v141
	v_mov_b32_e32 v147, v142
	v_mov_b32_e32 v141, v143
	v_pk_add_f32 v[144:145], v[170:171], v[144:145]
	v_pk_add_f32 v[140:141], v[146:147], v[140:141]
	v_pk_add_f32 v[144:145], v[144:145], v[144:145] op_sel:[0,1] op_sel_hi:[1,0]
	v_pk_add_f32 v[140:141], v[140:141], v[140:141] op_sel:[0,1] op_sel_hi:[1,0]
	v_add_f32_e32 v136, v136, v137
	v_add_f32_e32 v138, v138, v139
	v_mov_b32_e32 v145, v132
	v_mov_b32_e32 v141, v133
	v_mov_b32_e32 v137, v134
	v_mov_b32_e32 v139, v135
	v_pk_add_f32 v[132:133], v[144:145], v[140:141]
	v_pk_add_f32 v[134:135], v[136:137], v[138:139]
	s_lshl_b32 s10, s46, 1
	v_pk_add_f32 v[132:133], v[132:133], v[134:135]
	v_mov_b32_e32 v159, v149
	v_add_f32_e32 v132, v132, v133
	v_fmamk_f32 v132, v132, 0x3a800000, v180
	v_cmp_gt_f32_e32 vcc, s49, v132
	v_mul_f32_e32 v133, 0x4b800000, v132
	s_add_i32 s51, s51, 1
	v_cndmask_b32_e32 v132, v132, v133, vcc
	v_rsq_f32_e32 v132, v132
	s_nop 0
	v_mul_f32_e32 v133, 0x45800000, v132
	v_cndmask_b32_e32 v134, v132, v133, vcc
	v_mov_b32_e32 v132, v129
	v_mov_b32_e32 v133, v130
	v_mov_b32_e32 v129, v131
	v_pk_add_f32 v[128:129], v[132:133], v[128:129]
	v_and_b32_e32 v131, 64, v178
	v_add_f32_e32 v128, v128, v129
	v_mul_f32_e32 v129, v134, v134
	v_mul_f32_e32 v128, v128, v129
	v_fmamk_f32 v128, v128, 0x3b800000, v180
	v_cmp_gt_f32_e32 vcc, s49, v128
	v_mul_f32_e32 v129, 0x4b800000, v128
	v_add_u32_e32 v131, 64, v131
	v_cndmask_b32_e32 v128, v128, v129, vcc
	v_rsq_f32_e32 v128, v128
	s_nop 0
	v_mul_f32_e32 v129, 0x45800000, v128
	v_cndmask_b32_e32 v128, v128, v129, vcc
	v_max3_f32 v129, v112, s50, v113
	v_max3_f32 v129, v129, v114, v115
	v_max3_f32 v129, v129, v116, v117
	v_max3_f32 v129, v129, v118, v119
	v_max3_f32 v129, v129, v120, v121
	v_max3_f32 v129, v129, v122, v123
	v_max3_f32 v129, v129, v124, v125
	v_max3_f32 v129, v129, v126, v127
	v_max3_f32 v129, v129, v96, v97
	v_max3_f32 v129, v129, v98, v99
	v_max3_f32 v129, v129, v100, v101
	v_max3_f32 v129, v129, v102, v103
	v_max3_f32 v129, v129, v104, v105
	v_max3_f32 v129, v129, v106, v107
	v_max3_f32 v129, v129, v108, v109
	v_max3_f32 v129, v129, v110, v111
	v_max3_f32 v129, v129, v80, v81
	v_max3_f32 v129, v129, v82, v83
	v_max3_f32 v129, v129, v84, v85
	v_max3_f32 v129, v129, v86, v87
	v_max3_f32 v129, v129, v88, v89
	v_max3_f32 v129, v129, v90, v91
	v_max3_f32 v129, v129, v92, v93
	v_max3_f32 v129, v129, v94, v95
	v_max3_f32 v129, v129, v64, v65
	v_max3_f32 v129, v129, v66, v67
	v_max3_f32 v129, v129, v68, v69
	v_max3_f32 v129, v129, v70, v71
	v_max3_f32 v129, v129, v72, v73
	v_max3_f32 v129, v129, v74, v75
	v_max3_f32 v129, v129, v76, v77
	v_max3_f32 v129, v129, v78, v79
	v_max3_f32 v129, v129, v48, v49
	v_max3_f32 v129, v129, v50, v51
	v_max3_f32 v129, v129, v52, v53
	v_max3_f32 v129, v129, v54, v55
	v_max3_f32 v129, v129, v56, v57
	v_max3_f32 v129, v129, v58, v59
	v_max3_f32 v129, v129, v60, v61
	v_max3_f32 v129, v129, v62, v63
	v_max3_f32 v129, v129, v32, v33
	v_max3_f32 v129, v129, v34, v35
	v_max3_f32 v129, v129, v36, v37
	v_max3_f32 v129, v129, v38, v39
	v_max3_f32 v129, v129, v40, v41
	v_max3_f32 v129, v129, v42, v43
	v_max3_f32 v129, v129, v44, v45
	v_max3_f32 v129, v129, v46, v47
	v_max3_f32 v129, v129, v16, v17
	v_max3_f32 v129, v129, v18, v19
	v_max3_f32 v129, v129, v20, v21
	v_max3_f32 v129, v129, v22, v23
	v_max3_f32 v129, v129, v24, v25
	v_max3_f32 v129, v129, v26, v27
	v_max3_f32 v129, v129, v28, v29
	v_max3_f32 v129, v129, v30, v31
	v_max3_f32 v129, v129, v0, v1
	v_max3_f32 v129, v129, v2, v3
	v_max3_f32 v129, v129, v4, v5
	v_max3_f32 v129, v129, v6, v7
	v_max3_f32 v129, v129, v8, v9
	v_max3_f32 v129, v129, v10, v11
	v_mul_f32_e32 v128, v134, v128
	v_max3_f32 v129, v129, v12, v13
	v_max3_f32 v130, v129, v14, v15
	v_mul_f32_e32 v129, 0x3db8aa3b, v128
	v_xor_b32_e32 v128, 32, v178
	v_cmp_lt_i32_e32 vcc, v128, v131
	v_mul_f32_e32 v130, v129, v130
	s_nop 0
	v_cndmask_b32_e32 v128, v178, v128, vcc
	v_lshlrev_b32_e32 v128, 2, v128
	v_mov_b32_e32 v131, v130
	s_nop 1
	v_permlane32_swap_b32_e32 v131, v130
	s_waitcnt lgkmcnt(0)
	v_max_f32_e32 v130, v130, v131
	v_fma_f32 v112, v129, v112, -v130
	v_exp_f32_e32 v112, v112
	v_fma_f32 v113, v129, v113, -v130
	v_exp_f32_e32 v113, v113
	v_fma_f32 v114, v129, v114, -v130
	v_exp_f32_e32 v114, v114
	v_fma_f32 v115, v129, v115, -v130
	v_exp_f32_e32 v115, v115
	v_fma_f32 v116, v129, v116, -v130
	v_add_f32_e32 v131, 0, v112
	v_exp_f32_e32 v132, v116
	v_add_f32_e32 v131, v113, v131
	v_add_f32_e32 v131, v114, v131
	v_add_f32_e32 v131, v115, v131
	v_fma_f32 v117, v129, v117, -v130
	v_add_f32_e32 v116, v132, v131
	v_exp_f32_e32 v131, v117
	v_fma_f32 v117, v129, v118, -v130
	v_exp_f32_e32 v133, v117
	v_fma_f32 v117, v129, v119, -v130
	v_exp_f32_e32 v119, v117
	v_fma_f32 v117, v129, v120, -v130
	v_exp_f32_e32 v120, v117
	v_fma_f32 v117, v129, v121, -v130
	v_add_f32_e32 v116, v131, v116
	v_exp_f32_e32 v121, v117
	v_fma_f32 v117, v129, v122, -v130
	v_add_f32_e32 v116, v133, v116
	v_exp_f32_e32 v122, v117
	v_fma_f32 v117, v129, v123, -v130
	v_add_f32_e32 v116, v119, v116
	v_exp_f32_e32 v123, v117
	v_fma_f32 v117, v129, v124, -v130
	v_add_f32_e32 v116, v120, v116
	v_exp_f32_e32 v124, v117
	v_fma_f32 v117, v129, v125, -v130
	v_add_f32_e32 v116, v121, v116
	v_exp_f32_e32 v125, v117
	v_fma_f32 v117, v129, v126, -v130
	v_add_f32_e32 v116, v122, v116
	v_exp_f32_e32 v126, v117
	v_fma_f32 v117, v129, v127, -v130
	v_add_f32_e32 v116, v123, v116
	v_exp_f32_e32 v127, v117
	v_fma_f32 v96, v129, v96, -v130
	v_add_f32_e32 v116, v124, v116
	v_exp_f32_e32 v96, v96
	v_fma_f32 v97, v129, v97, -v130
	v_add_f32_e32 v116, v125, v116
	v_exp_f32_e32 v97, v97
	v_fma_f32 v98, v129, v98, -v130
	v_add_f32_e32 v116, v126, v116
	v_exp_f32_e32 v98, v98
	v_fma_f32 v99, v129, v99, -v130
	v_add_f32_e32 v134, v127, v116
	v_exp_f32_e32 v99, v99
	v_fma_f32 v100, v129, v100, -v130
	v_cvt_pk_bf16_f32 v116, v112, v113
	v_cvt_pk_bf16_f32 v112, v120, v121
	v_add_f32_e32 v120, v96, v134
	v_exp_f32_e32 v121, v100
	v_add_f32_e32 v120, v97, v120
	v_add_f32_e32 v120, v98, v120
	v_add_f32_e32 v120, v99, v120
	v_fma_f32 v101, v129, v101, -v130
	v_add_f32_e32 v100, v121, v120
	v_exp_f32_e32 v120, v101
	v_fma_f32 v101, v129, v102, -v130
	v_cvt_pk_bf16_f32 v113, v122, v123
	v_exp_f32_e32 v122, v101
	v_fma_f32 v101, v129, v103, -v130
	v_exp_f32_e32 v103, v101
	v_fma_f32 v101, v129, v104, -v130
	v_exp_f32_e32 v104, v101
	v_fma_f32 v101, v129, v105, -v130
	v_add_f32_e32 v100, v120, v100
	v_exp_f32_e32 v105, v101
	v_fma_f32 v101, v129, v106, -v130
	v_add_f32_e32 v100, v122, v100
	v_exp_f32_e32 v106, v101
	v_fma_f32 v101, v129, v107, -v130
	v_add_f32_e32 v100, v103, v100
	v_exp_f32_e32 v107, v101
	v_fma_f32 v101, v129, v108, -v130
	v_add_f32_e32 v100, v104, v100
	v_exp_f32_e32 v108, v101
	v_fma_f32 v101, v129, v109, -v130
	v_add_f32_e32 v100, v105, v100
	v_exp_f32_e32 v109, v101
	v_fma_f32 v101, v129, v110, -v130
	v_add_f32_e32 v100, v106, v100
	v_exp_f32_e32 v110, v101
	v_fma_f32 v101, v129, v111, -v130
	v_add_f32_e32 v100, v107, v100
	v_exp_f32_e32 v111, v101
	v_fma_f32 v80, v129, v80, -v130
	v_add_f32_e32 v100, v108, v100
	v_exp_f32_e32 v80, v80
	v_fma_f32 v81, v129, v81, -v130
	v_add_f32_e32 v100, v109, v100
	v_exp_f32_e32 v81, v81
	v_fma_f32 v82, v129, v82, -v130
	v_add_f32_e32 v100, v110, v100
	v_exp_f32_e32 v82, v82
	v_fma_f32 v83, v129, v83, -v130
	v_add_f32_e32 v123, v111, v100
	v_exp_f32_e32 v83, v83
	v_fma_f32 v84, v129, v84, -v130
	v_cvt_pk_bf16_f32 v100, v96, v97
	v_cvt_pk_bf16_f32 v96, v104, v105
	v_add_f32_e32 v104, v80, v123
	v_exp_f32_e32 v105, v84
	v_add_f32_e32 v104, v81, v104
	v_add_f32_e32 v104, v82, v104
	v_add_f32_e32 v104, v83, v104
	v_fma_f32 v85, v129, v85, -v130
	v_add_f32_e32 v84, v105, v104
	v_exp_f32_e32 v104, v85
	v_fma_f32 v85, v129, v86, -v130
	v_cvt_pk_bf16_f32 v97, v106, v107
	v_exp_f32_e32 v106, v85
	v_fma_f32 v85, v129, v87, -v130
	v_exp_f32_e32 v87, v85
	v_fma_f32 v85, v129, v88, -v130
	v_exp_f32_e32 v88, v85
	v_fma_f32 v85, v129, v89, -v130
	v_add_f32_e32 v84, v104, v84
	v_exp_f32_e32 v89, v85
	v_fma_f32 v85, v129, v90, -v130
	v_add_f32_e32 v84, v106, v84
	v_exp_f32_e32 v90, v85
	v_fma_f32 v85, v129, v91, -v130
	v_add_f32_e32 v84, v87, v84
	v_exp_f32_e32 v91, v85
	v_fma_f32 v85, v129, v92, -v130
	v_add_f32_e32 v84, v88, v84
	v_exp_f32_e32 v92, v85
	v_fma_f32 v85, v129, v93, -v130
	v_add_f32_e32 v84, v89, v84
	v_exp_f32_e32 v93, v85
	v_fma_f32 v85, v129, v94, -v130
	v_add_f32_e32 v84, v90, v84
	v_exp_f32_e32 v94, v85
	v_fma_f32 v85, v129, v95, -v130
	v_add_f32_e32 v84, v91, v84
	v_exp_f32_e32 v95, v85
	v_fma_f32 v64, v129, v64, -v130
	v_add_f32_e32 v84, v92, v84
	v_exp_f32_e32 v64, v64
	v_fma_f32 v65, v129, v65, -v130
	v_add_f32_e32 v84, v93, v84
	v_exp_f32_e32 v65, v65
	v_fma_f32 v66, v129, v66, -v130
	v_add_f32_e32 v84, v94, v84
	v_exp_f32_e32 v66, v66
	v_fma_f32 v67, v129, v67, -v130
	v_add_f32_e32 v107, v95, v84
	v_exp_f32_e32 v67, v67
	v_fma_f32 v68, v129, v68, -v130
	v_cvt_pk_bf16_f32 v84, v80, v81
	v_cvt_pk_bf16_f32 v80, v88, v89
	v_add_f32_e32 v88, v64, v107
	v_exp_f32_e32 v89, v68
	v_add_f32_e32 v88, v65, v88
	v_add_f32_e32 v88, v66, v88
	v_add_f32_e32 v88, v67, v88
	v_fma_f32 v69, v129, v69, -v130
	v_add_f32_e32 v68, v89, v88
	v_exp_f32_e32 v88, v69
	v_fma_f32 v69, v129, v70, -v130
	v_cvt_pk_bf16_f32 v81, v90, v91
	v_exp_f32_e32 v90, v69
	v_fma_f32 v69, v129, v71, -v130
	v_exp_f32_e32 v71, v69
	v_fma_f32 v69, v129, v72, -v130
	v_exp_f32_e32 v72, v69
	v_fma_f32 v69, v129, v73, -v130
	v_add_f32_e32 v68, v88, v68
	v_exp_f32_e32 v73, v69
	v_fma_f32 v69, v129, v74, -v130
	v_add_f32_e32 v68, v90, v68
	v_exp_f32_e32 v74, v69
	v_fma_f32 v69, v129, v75, -v130
	v_add_f32_e32 v68, v71, v68
	v_exp_f32_e32 v75, v69
	v_fma_f32 v69, v129, v76, -v130
	v_add_f32_e32 v68, v72, v68
	v_exp_f32_e32 v76, v69
	v_fma_f32 v69, v129, v77, -v130
	v_add_f32_e32 v68, v73, v68
	v_exp_f32_e32 v77, v69
	v_fma_f32 v69, v129, v78, -v130
	v_add_f32_e32 v68, v74, v68
	v_exp_f32_e32 v78, v69
	v_fma_f32 v69, v129, v79, -v130
	v_add_f32_e32 v68, v75, v68
	v_exp_f32_e32 v79, v69
	v_fma_f32 v48, v129, v48, -v130
	v_add_f32_e32 v68, v76, v68
	v_exp_f32_e32 v48, v48
	v_fma_f32 v49, v129, v49, -v130
	v_add_f32_e32 v68, v77, v68
	v_exp_f32_e32 v49, v49
	v_fma_f32 v50, v129, v50, -v130
	v_add_f32_e32 v68, v78, v68
	v_exp_f32_e32 v50, v50
	v_fma_f32 v51, v129, v51, -v130
	v_add_f32_e32 v91, v79, v68
	v_exp_f32_e32 v51, v51
	v_fma_f32 v52, v129, v52, -v130
	v_cvt_pk_bf16_f32 v68, v64, v65
	v_cvt_pk_bf16_f32 v64, v72, v73
	v_add_f32_e32 v72, v48, v91
	v_exp_f32_e32 v73, v52
	v_add_f32_e32 v72, v49, v72
	v_add_f32_e32 v72, v50, v72
	v_add_f32_e32 v72, v51, v72
	v_fma_f32 v53, v129, v53, -v130
	v_add_f32_e32 v52, v73, v72
	v_exp_f32_e32 v72, v53
	v_fma_f32 v53, v129, v54, -v130
	v_cvt_pk_bf16_f32 v65, v74, v75
	v_exp_f32_e32 v74, v53
	v_fma_f32 v53, v129, v55, -v130
	v_exp_f32_e32 v55, v53
	v_fma_f32 v53, v129, v56, -v130
	v_exp_f32_e32 v56, v53
	v_fma_f32 v53, v129, v57, -v130
	v_add_f32_e32 v52, v72, v52
	v_exp_f32_e32 v57, v53
	v_fma_f32 v53, v129, v58, -v130
	v_add_f32_e32 v52, v74, v52
	v_exp_f32_e32 v58, v53
	v_fma_f32 v53, v129, v59, -v130
	v_add_f32_e32 v52, v55, v52
	v_exp_f32_e32 v59, v53
	v_fma_f32 v53, v129, v60, -v130
	v_add_f32_e32 v52, v56, v52
	v_exp_f32_e32 v60, v53
	v_fma_f32 v53, v129, v61, -v130
	v_add_f32_e32 v52, v57, v52
	v_exp_f32_e32 v61, v53
	v_fma_f32 v53, v129, v62, -v130
	v_add_f32_e32 v52, v58, v52
	v_exp_f32_e32 v62, v53
	v_fma_f32 v53, v129, v63, -v130
	v_add_f32_e32 v52, v59, v52
	v_exp_f32_e32 v63, v53
	v_fma_f32 v32, v129, v32, -v130
	v_add_f32_e32 v52, v60, v52
	v_exp_f32_e32 v32, v32
	v_fma_f32 v33, v129, v33, -v130
	v_add_f32_e32 v52, v61, v52
	v_exp_f32_e32 v33, v33
	v_fma_f32 v34, v129, v34, -v130
	v_add_f32_e32 v52, v62, v52
	v_exp_f32_e32 v34, v34
	v_fma_f32 v35, v129, v35, -v130
	v_add_f32_e32 v75, v63, v52
	v_exp_f32_e32 v35, v35
	v_fma_f32 v36, v129, v36, -v130
	v_cvt_pk_bf16_f32 v52, v48, v49
	v_cvt_pk_bf16_f32 v48, v56, v57
	v_add_f32_e32 v56, v32, v75
	v_exp_f32_e32 v57, v36
	v_add_f32_e32 v56, v33, v56
	v_add_f32_e32 v56, v34, v56
	v_add_f32_e32 v56, v35, v56
	v_fma_f32 v37, v129, v37, -v130
	v_add_f32_e32 v36, v57, v56
	v_exp_f32_e32 v56, v37
	v_fma_f32 v37, v129, v38, -v130
	v_cvt_pk_bf16_f32 v49, v58, v59
	v_exp_f32_e32 v58, v37
	v_fma_f32 v37, v129, v39, -v130
	v_exp_f32_e32 v39, v37
	v_fma_f32 v37, v129, v40, -v130
	v_exp_f32_e32 v40, v37
	v_fma_f32 v37, v129, v41, -v130
	v_add_f32_e32 v36, v56, v36
	v_exp_f32_e32 v41, v37
	v_fma_f32 v37, v129, v42, -v130
	v_add_f32_e32 v36, v58, v36
	v_exp_f32_e32 v42, v37
	v_fma_f32 v37, v129, v43, -v130
	v_add_f32_e32 v36, v39, v36
	v_exp_f32_e32 v43, v37
	v_fma_f32 v37, v129, v44, -v130
	v_add_f32_e32 v36, v40, v36
	v_exp_f32_e32 v44, v37
	v_fma_f32 v37, v129, v45, -v130
	v_add_f32_e32 v36, v41, v36
	v_exp_f32_e32 v45, v37
	v_fma_f32 v37, v129, v46, -v130
	v_add_f32_e32 v36, v42, v36
	v_exp_f32_e32 v46, v37
	v_fma_f32 v37, v129, v47, -v130
	v_add_f32_e32 v36, v43, v36
	v_exp_f32_e32 v47, v37
	v_fma_f32 v16, v129, v16, -v130
	v_add_f32_e32 v36, v44, v36
	v_exp_f32_e32 v16, v16
	v_fma_f32 v17, v129, v17, -v130
	v_add_f32_e32 v36, v45, v36
	v_exp_f32_e32 v17, v17
	v_fma_f32 v18, v129, v18, -v130
	v_add_f32_e32 v36, v46, v36
	v_exp_f32_e32 v18, v18
	v_fma_f32 v19, v129, v19, -v130
	v_add_f32_e32 v59, v47, v36
	v_exp_f32_e32 v19, v19
	v_fma_f32 v20, v129, v20, -v130
	v_cvt_pk_bf16_f32 v36, v32, v33
	v_cvt_pk_bf16_f32 v32, v40, v41
	v_add_f32_e32 v40, v16, v59
	v_exp_f32_e32 v41, v20
	v_add_f32_e32 v40, v17, v40
	v_add_f32_e32 v40, v18, v40
	v_add_f32_e32 v40, v19, v40
	v_fma_f32 v21, v129, v21, -v130
	v_add_f32_e32 v20, v41, v40
	v_exp_f32_e32 v40, v21
	v_fma_f32 v21, v129, v22, -v130
	v_cvt_pk_bf16_f32 v33, v42, v43
	v_exp_f32_e32 v42, v21
	v_fma_f32 v21, v129, v23, -v130
	v_exp_f32_e32 v23, v21
	v_fma_f32 v21, v129, v24, -v130
	v_exp_f32_e32 v24, v21
	v_fma_f32 v21, v129, v25, -v130
	v_add_f32_e32 v20, v40, v20
	v_exp_f32_e32 v25, v21
	v_fma_f32 v21, v129, v26, -v130
	v_add_f32_e32 v20, v42, v20
	v_exp_f32_e32 v26, v21
	v_fma_f32 v21, v129, v27, -v130
	v_add_f32_e32 v20, v23, v20
	v_exp_f32_e32 v27, v21
	v_fma_f32 v21, v129, v28, -v130
	v_add_f32_e32 v20, v24, v20
	v_exp_f32_e32 v28, v21
	v_fma_f32 v21, v129, v29, -v130
	v_add_f32_e32 v20, v25, v20
	v_exp_f32_e32 v29, v21
	v_fma_f32 v21, v129, v30, -v130
	v_add_f32_e32 v20, v26, v20
	v_exp_f32_e32 v30, v21
	v_fma_f32 v21, v129, v31, -v130
	v_add_f32_e32 v20, v27, v20
	v_exp_f32_e32 v31, v21
	v_fma_f32 v0, v129, v0, -v130
	v_add_f32_e32 v20, v28, v20
	v_exp_f32_e32 v0, v0
	v_fma_f32 v1, v129, v1, -v130
	v_add_f32_e32 v20, v29, v20
	v_exp_f32_e32 v1, v1
	v_fma_f32 v2, v129, v2, -v130
	v_add_f32_e32 v20, v30, v20
	v_exp_f32_e32 v2, v2
	v_fma_f32 v3, v129, v3, -v130
	v_add_f32_e32 v43, v31, v20
	v_exp_f32_e32 v3, v3
	v_fma_f32 v4, v129, v4, -v130
	v_cvt_pk_bf16_f32 v20, v16, v17
	v_cvt_pk_bf16_f32 v16, v24, v25
	v_add_f32_e32 v24, v0, v43
	v_exp_f32_e32 v4, v4
	v_fma_f32 v5, v129, v5, -v130
	v_add_f32_e32 v24, v1, v24
	v_exp_f32_e32 v5, v5
	v_fma_f32 v6, v129, v6, -v130
	v_add_f32_e32 v24, v2, v24
	v_exp_f32_e32 v6, v6
	v_fma_f32 v7, v129, v7, -v130
	v_add_f32_e32 v24, v3, v24
	v_exp_f32_e32 v7, v7
	v_fma_f32 v8, v129, v8, -v130
	v_add_f32_e32 v24, v4, v24
	v_exp_f32_e32 v8, v8
	v_fma_f32 v9, v129, v9, -v130
	v_add_f32_e32 v24, v5, v24
	v_exp_f32_e32 v9, v9
	v_fma_f32 v10, v129, v10, -v130
	v_add_f32_e32 v24, v6, v24
	v_exp_f32_e32 v10, v10
	v_fma_f32 v11, v129, v11, -v130
	v_add_f32_e32 v24, v7, v24
	v_exp_f32_e32 v11, v11
	v_fma_f32 v12, v129, v12, -v130
	v_add_f32_e32 v24, v8, v24
	v_exp_f32_e32 v12, v12
	v_fma_f32 v13, v129, v13, -v130
	v_add_f32_e32 v24, v9, v24
	v_exp_f32_e32 v13, v13
	v_fma_f32 v14, v129, v14, -v130
	v_add_f32_e32 v24, v10, v24
	v_exp_f32_e32 v14, v14
	v_fma_f32 v15, v129, v15, -v130
	v_add_f32_e32 v24, v11, v24
	v_exp_f32_e32 v15, v15
	v_add_f32_e32 v24, v12, v24
	v_add_f32_e32 v24, v13, v24
	v_add_f32_e32 v24, v14, v24
	v_cvt_pk_bf16_f32 v22, v41, v40
	v_add_f32_e32 v40, v15, v24
	v_cvt_pk_bf16_f32 v21, v18, v19
	v_cvt_pk_bf16_f32 v18, v28, v29
	v_cvt_pk_bf16_f32 v28, v0, v1
	ds_bpermute_b32 v0, v128, v40
	v_cvt_pk_bf16_f32 v117, v114, v115
	v_cvt_pk_bf16_f32 v118, v132, v131
	v_cvt_pk_bf16_f32 v119, v133, v119
	v_cvt_pk_bf16_f32 v114, v124, v125
	v_cvt_pk_bf16_f32 v115, v126, v127
	v_cvt_pk_bf16_f32 v101, v98, v99
	v_cvt_pk_bf16_f32 v102, v121, v120
	v_cvt_pk_bf16_f32 v103, v122, v103
	v_cvt_pk_bf16_f32 v98, v108, v109
	v_cvt_pk_bf16_f32 v99, v110, v111
	v_cvt_pk_bf16_f32 v85, v82, v83
	v_cvt_pk_bf16_f32 v86, v105, v104
	v_cvt_pk_bf16_f32 v87, v106, v87
	v_cvt_pk_bf16_f32 v82, v92, v93
	v_cvt_pk_bf16_f32 v83, v94, v95
	v_cvt_pk_bf16_f32 v69, v66, v67
	v_cvt_pk_bf16_f32 v70, v89, v88
	v_cvt_pk_bf16_f32 v71, v90, v71
	v_cvt_pk_bf16_f32 v66, v76, v77
	v_cvt_pk_bf16_f32 v67, v78, v79
	v_cvt_pk_bf16_f32 v53, v50, v51
	v_cvt_pk_bf16_f32 v54, v73, v72
	v_cvt_pk_bf16_f32 v55, v74, v55
	v_cvt_pk_bf16_f32 v50, v60, v61
	v_cvt_pk_bf16_f32 v51, v62, v63
	v_cvt_pk_bf16_f32 v37, v34, v35
	v_cvt_pk_bf16_f32 v38, v57, v56
	v_cvt_pk_bf16_f32 v39, v58, v39
	v_cvt_pk_bf16_f32 v34, v44, v45
	v_cvt_pk_bf16_f32 v35, v46, v47
	v_cvt_pk_bf16_f32 v23, v42, v23
	v_cvt_pk_bf16_f32 v17, v26, v27
	v_cvt_pk_bf16_f32 v19, v30, v31
	v_cvt_pk_bf16_f32 v29, v2, v3
	v_cvt_pk_bf16_f32 v30, v4, v5
	v_cvt_pk_bf16_f32 v31, v6, v7
	v_cvt_pk_bf16_f32 v24, v8, v9
	v_cvt_pk_bf16_f32 v25, v10, v11
	v_cvt_pk_bf16_f32 v26, v12, v13
	v_cvt_pk_bf16_f32 v27, v14, v15
	v_lshl_add_u64 v[60:61], v[160:161], 0, s[38:39]
	s_waitcnt lgkmcnt(0)
	v_add_f32_e32 v72, v40, v0
	s_barrier
	s_waitcnt vmcnt(0)
	ds_write_b128 v172, v[228:231]
	ds_write_b128 v172, v[224:227] offset:128
	ds_write_b128 v172, v[216:219] offset:256
	ds_write_b128 v172, v[212:215] offset:384
	ds_write_b128 v172, v[232:235] offset:35840
	ds_write_b128 v172, v[246:249] offset:35968
	ds_write_b128 v172, v[240:243] offset:36096
	ds_write_b128 v172, v[236:239] offset:36224
	v_lshl_add_u64 v[12:13], v[160:161], 0, s[40:41]
	v_lshl_add_u64 v[60:61], v[160:161], 0, s[44:45]
	global_load_dwordx4 v[0:3], v[164:165], off offset:2048
	global_load_dwordx4 v[4:7], v[12:13], off offset:384
	global_load_dwordx4 v[8:11], v[12:13], off offset:256
	s_nop 0
	global_load_dwordx4 v[12:15], v[12:13], off offset:128
	s_nop 0
	global_load_dwordx4 v[40:43], v[166:167], off offset:2048
	global_load_dwordx4 v[44:47], v[60:61], off offset:384
	global_load_dwordx4 v[56:59], v[60:61], off offset:256
	s_nop 0
	global_load_dwordx4 v[60:63], v[60:61], off offset:128
	s_waitcnt vmcnt(7)
	ds_write_b128 v173, v[0:3]
	s_waitcnt vmcnt(4)
	ds_write_b128 v174, v[12:15]
	ds_write_b128 v175, v[8:11]
	ds_write_b128 v179, v[4:7]
	s_waitcnt vmcnt(3)
	ds_write_b128 v182, v[40:43]
	s_waitcnt vmcnt(0)
	ds_write_b128 v183, v[60:63]
	ds_write_b128 v184, v[56:59]
	ds_write_b128 v185, v[44:47]
	v_div_scale_f32 v0, s[4:5], v72, v72, 1.0
	v_rcp_f32_e32 v1, v0
	s_waitcnt lgkmcnt(0)
	s_barrier
	v_fma_f32 v2, -v0, v1, 1.0
	v_fmac_f32_e32 v1, v2, v1
	v_div_scale_f32 v2, vcc, 1.0, v72, 1.0
	v_mul_f32_e32 v3, v2, v1
	v_fma_f32 v4, -v0, v3, v2
	v_fmac_f32_e32 v3, v4, v1
	v_fma_f32 v0, -v0, v3, v2
	v_div_fmas_f32 v0, v0, v1, v3
	v_div_fixup_f32 v44, v0, v72, 1.0
	v_lshl_add_u64 v[0:1], s[12:13], 0, v[162:163]
	v_lshl_add_u64 v[0:1], v[0:1], 0, s[10:11]
	v_lshl_add_u64 v[46:47], v[0:1], 0, v[158:159]
	v_mbcnt_lo_u32_b32 v40, -1, 0
	v_mbcnt_hi_u32_b32 v40, -1, v40
	v_and_b32_e32 v40, 32, v40
	v_lshrrev_b32_e32 v40, 2, v40
	v_mov_b32_e32 v41, 0
	v_lshl_add_u64 v[124:125], v[46:47], 0, v[40:41]
	ds_read_b64_tr_b16 v[56:57], v186
	ds_read_b64_tr_b16 v[58:59], v186 offset:4480
	ds_read_b64_tr_b16 v[60:61], v186 offset:8960
	ds_read_b64_tr_b16 v[62:63], v186 offset:13440
	ds_read_b64_tr_b16 v[88:89], v186 offset:17920
	ds_read_b64_tr_b16 v[90:91], v186 offset:22400
	ds_read_b64_tr_b16 v[92:93], v186 offset:26880
	ds_read_b64_tr_b16 v[94:95], v186 offset:31360
	ds_read_b64_tr_b16 v[104:105], v186 offset:35840
	ds_read_b64_tr_b16 v[106:107], v186 offset:40320
	ds_read_b64_tr_b16 v[108:109], v186 offset:44800
	ds_read_b64_tr_b16 v[110:111], v186 offset:49280
	ds_read_b64_tr_b16 v[120:121], v186 offset:53760
	ds_read_b64_tr_b16 v[122:123], v186 offset:58240
	s_mov_b64 s[4:5], 0
	s_waitcnt lgkmcnt(12)
	v_mfma_f32_32x32x16_bf16 v[0:15], v[56:59], v[116:119], 0
	v_add_u32_e32 v40, v187, v177
	ds_read_b64_tr_b16 v[56:57], v186 offset:62720
	ds_read_b64_tr_b16 v[58:59], v40
	s_waitcnt lgkmcnt(12)
	v_mfma_f32_32x32x16_bf16 v[0:15], v[60:63], v[112:115], v[0:15]
	v_add_u32_e32 v40, v188, v177
	v_add_u32_e32 v42, v189, v177
	ds_read_b64_tr_b16 v[60:61], v40
	ds_read_b64_tr_b16 v[62:63], v42
	s_waitcnt lgkmcnt(12)
	v_mfma_f32_32x32x16_bf16 v[0:15], v[88:91], v[100:103], v[0:15]
	v_add_u32_e32 v40, v190, v177
	v_add_u32_e32 v42, v191, v177
	ds_read_b64_tr_b16 v[88:89], v40
	ds_read_b64_tr_b16 v[90:91], v42
	s_waitcnt lgkmcnt(12)
	v_mfma_f32_32x32x16_bf16 v[0:15], v[92:95], v[96:99], v[0:15]
	v_add_u32_e32 v40, v192, v177
	v_add_u32_e32 v42, v193, v177
	ds_read_b64_tr_b16 v[92:93], v40
	ds_read_b64_tr_b16 v[94:95], v42
	s_waitcnt lgkmcnt(12)
	v_mfma_f32_32x32x16_bf16 v[0:15], v[104:107], v[84:87], v[0:15]
	v_add_u32_e32 v40, v194, v177
	v_add_u32_e32 v42, v195, v177
	ds_read_b64_tr_b16 v[104:105], v40
	ds_read_b64_tr_b16 v[106:107], v42
	s_waitcnt lgkmcnt(12)
	v_mfma_f32_32x32x16_bf16 v[0:15], v[108:111], v[80:83], v[0:15]
	v_add_u32_e32 v40, v196, v177
	v_add_u32_e32 v42, v197, v177
	ds_read_b64_tr_b16 v[108:109], v40
	ds_read_b64_tr_b16 v[110:111], v42
	s_waitcnt lgkmcnt(12)
	v_mfma_f32_32x32x16_bf16 v[0:15], v[120:123], v[68:71], v[0:15]
	v_add_u32_e32 v40, v198, v177
	v_add_u32_e32 v42, v199, v177
	ds_read_b64_tr_b16 v[120:121], v40
	ds_read_b64_tr_b16 v[122:123], v42
	s_waitcnt lgkmcnt(12)
	v_mfma_f32_32x32x16_bf16 v[0:15], v[56:59], v[64:67], v[0:15]
	v_add_u32_e32 v40, v200, v177
	v_add_u32_e32 v42, v201, v177
	ds_read_b64_tr_b16 v[56:57], v40
	ds_read_b64_tr_b16 v[58:59], v42
	s_waitcnt lgkmcnt(12)
	v_mfma_f32_32x32x16_bf16 v[0:15], v[60:63], v[52:55], v[0:15]
	v_add_u32_e32 v40, v202, v177
	v_add_u32_e32 v42, v203, v177
	ds_read_b64_tr_b16 v[60:61], v40
	ds_read_b64_tr_b16 v[62:63], v42
	s_waitcnt lgkmcnt(12)
	v_mfma_f32_32x32x16_bf16 v[0:15], v[88:91], v[48:51], v[0:15]
	ds_read_b64_tr_b16 v[88:89], v186 offset:64
	ds_read_b64_tr_b16 v[90:91], v186 offset:4544
	s_waitcnt lgkmcnt(12)
	v_mfma_f32_32x32x16_bf16 v[0:15], v[92:95], v[36:39], v[0:15]
	ds_read_b64_tr_b16 v[92:93], v186 offset:9024
	ds_read_b64_tr_b16 v[94:95], v186 offset:13504
	s_waitcnt lgkmcnt(12)
	v_mfma_f32_32x32x16_bf16 v[0:15], v[104:107], v[32:35], v[0:15]
	ds_read_b64_tr_b16 v[104:105], v186 offset:17984
	ds_read_b64_tr_b16 v[106:107], v186 offset:22464
	s_waitcnt lgkmcnt(12)
	v_mfma_f32_32x32x16_bf16 v[0:15], v[108:111], v[20:23], v[0:15]
	ds_read_b64_tr_b16 v[108:109], v186 offset:26944
	ds_read_b64_tr_b16 v[110:111], v186 offset:31424
	s_waitcnt lgkmcnt(12)
	v_mfma_f32_32x32x16_bf16 v[0:15], v[120:123], v[16:19], v[0:15]
	ds_read_b64_tr_b16 v[120:121], v186 offset:35904
	ds_read_b64_tr_b16 v[122:123], v186 offset:40384
	s_waitcnt lgkmcnt(12)
	v_mfma_f32_32x32x16_bf16 v[0:15], v[56:59], v[28:31], v[0:15]
	ds_read_b64_tr_b16 v[56:57], v186 offset:44864
	ds_read_b64_tr_b16 v[58:59], v186 offset:49344
	s_waitcnt lgkmcnt(12)
	v_mfma_f32_32x32x16_bf16 v[0:15], v[60:63], v[24:27], v[0:15]
	ds_read_b64_tr_b16 v[60:61], v186 offset:53824
	ds_read_b64_tr_b16 v[62:63], v186 offset:58304
	s_nop 11
	v_pk_mul_f32 v[0:1], v[0:1], v[44:45] op_sel_hi:[1,0]
	v_pk_mul_f32 v[2:3], v[2:3], v[44:45] op_sel_hi:[1,0]
	v_pk_mul_f32 v[4:5], v[4:5], v[44:45] op_sel_hi:[1,0]
	v_pk_mul_f32 v[6:7], v[6:7], v[44:45] op_sel_hi:[1,0]
	v_cvt_pk_bf16_f32 v0, v0, v1
	v_cvt_pk_bf16_f32 v1, v2, v3
	v_cvt_pk_bf16_f32 v2, v4, v5
	v_cvt_pk_bf16_f32 v3, v6, v7
	s_nop 1
	v_permlane32_swap_b32_e32 v0, v2
	v_permlane32_swap_b32_e32 v1, v3
	global_store_dwordx4 v[124:125], v[0:3], off
	v_pk_mul_f32 v[8:9], v[8:9], v[44:45] op_sel_hi:[1,0]
	v_pk_mul_f32 v[10:11], v[10:11], v[44:45] op_sel_hi:[1,0]
	v_pk_mul_f32 v[12:13], v[12:13], v[44:45] op_sel_hi:[1,0]
	v_pk_mul_f32 v[14:15], v[14:15], v[44:45] op_sel_hi:[1,0]
	v_cvt_pk_bf16_f32 v4, v8, v9
	v_cvt_pk_bf16_f32 v5, v10, v11
	v_cvt_pk_bf16_f32 v6, v12, v13
	v_cvt_pk_bf16_f32 v7, v14, v15
	s_nop 1
	v_permlane32_swap_b32_e32 v4, v6
	v_permlane32_swap_b32_e32 v5, v7
	global_store_dwordx4 v[124:125], v[4:7], off offset:32
	s_nop 1
	s_waitcnt lgkmcnt(12)
	v_mfma_f32_32x32x16_bf16 v[0:15], v[88:91], v[116:119], 0
	v_add_u32_e32 v40, v187, v204
	ds_read_b64_tr_b16 v[88:89], v186 offset:62784
	ds_read_b64_tr_b16 v[90:91], v40
	s_waitcnt lgkmcnt(12)
	v_mfma_f32_32x32x16_bf16 v[0:15], v[92:95], v[112:115], v[0:15]
	v_add_u32_e32 v40, v188, v204
	v_add_u32_e32 v42, v189, v204
	ds_read_b64_tr_b16 v[92:93], v40
	ds_read_b64_tr_b16 v[94:95], v42
	s_waitcnt lgkmcnt(12)
	v_mfma_f32_32x32x16_bf16 v[0:15], v[104:107], v[100:103], v[0:15]
	v_add_u32_e32 v40, v190, v204
	v_add_u32_e32 v42, v191, v204
	ds_read_b64_tr_b16 v[104:105], v40
	ds_read_b64_tr_b16 v[106:107], v42
	s_waitcnt lgkmcnt(12)
	v_mfma_f32_32x32x16_bf16 v[0:15], v[108:111], v[96:99], v[0:15]
	v_add_u32_e32 v40, v192, v204
	v_add_u32_e32 v42, v193, v204
	ds_read_b64_tr_b16 v[108:109], v40
	ds_read_b64_tr_b16 v[110:111], v42
	s_waitcnt lgkmcnt(12)
	v_mfma_f32_32x32x16_bf16 v[0:15], v[120:123], v[84:87], v[0:15]
	v_add_u32_e32 v40, v194, v204
	v_add_u32_e32 v42, v195, v204
	ds_read_b64_tr_b16 v[120:121], v40
	ds_read_b64_tr_b16 v[122:123], v42
	s_waitcnt lgkmcnt(12)
	v_mfma_f32_32x32x16_bf16 v[0:15], v[56:59], v[80:83], v[0:15]
	v_add_u32_e32 v40, v196, v204
	v_add_u32_e32 v42, v197, v204
	ds_read_b64_tr_b16 v[56:57], v40
	ds_read_b64_tr_b16 v[58:59], v42
	s_waitcnt lgkmcnt(12)
	v_mfma_f32_32x32x16_bf16 v[0:15], v[60:63], v[68:71], v[0:15]
	v_add_u32_e32 v40, v198, v204
	v_add_u32_e32 v42, v199, v204
	ds_read_b64_tr_b16 v[60:61], v40
	ds_read_b64_tr_b16 v[62:63], v42
	s_waitcnt lgkmcnt(12)
	v_mfma_f32_32x32x16_bf16 v[0:15], v[88:91], v[64:67], v[0:15]
	v_add_u32_e32 v40, v200, v204
	v_add_u32_e32 v42, v201, v204
	ds_read_b64_tr_b16 v[88:89], v40
	ds_read_b64_tr_b16 v[90:91], v42
	s_waitcnt lgkmcnt(12)
	v_mfma_f32_32x32x16_bf16 v[0:15], v[92:95], v[52:55], v[0:15]
	v_add_u32_e32 v40, v202, v204
	v_add_u32_e32 v42, v203, v204
	ds_read_b64_tr_b16 v[92:93], v40
	ds_read_b64_tr_b16 v[94:95], v42
	s_waitcnt lgkmcnt(12)
	v_mfma_f32_32x32x16_bf16 v[0:15], v[104:107], v[48:51], v[0:15]
	ds_read_b64_tr_b16 v[104:105], v186 offset:128
	ds_read_b64_tr_b16 v[106:107], v186 offset:4608
	s_waitcnt lgkmcnt(12)
	v_mfma_f32_32x32x16_bf16 v[0:15], v[108:111], v[36:39], v[0:15]
	ds_read_b64_tr_b16 v[108:109], v186 offset:9088
	ds_read_b64_tr_b16 v[110:111], v186 offset:13568
	s_waitcnt lgkmcnt(12)
	v_mfma_f32_32x32x16_bf16 v[0:15], v[120:123], v[32:35], v[0:15]
	ds_read_b64_tr_b16 v[120:121], v186 offset:18048
	ds_read_b64_tr_b16 v[122:123], v186 offset:22528
	s_waitcnt lgkmcnt(12)
	v_mfma_f32_32x32x16_bf16 v[0:15], v[56:59], v[20:23], v[0:15]
	ds_read_b64_tr_b16 v[56:57], v186 offset:27008
	ds_read_b64_tr_b16 v[58:59], v186 offset:31488
	s_waitcnt lgkmcnt(12)
	v_mfma_f32_32x32x16_bf16 v[0:15], v[60:63], v[16:19], v[0:15]
	ds_read_b64_tr_b16 v[60:61], v186 offset:35968
	ds_read_b64_tr_b16 v[62:63], v186 offset:40448
	s_waitcnt lgkmcnt(12)
	v_mfma_f32_32x32x16_bf16 v[0:15], v[88:91], v[28:31], v[0:15]
	ds_read_b64_tr_b16 v[88:89], v186 offset:44928
	ds_read_b64_tr_b16 v[90:91], v186 offset:49408
	s_waitcnt lgkmcnt(12)
	v_mfma_f32_32x32x16_bf16 v[0:15], v[92:95], v[24:27], v[0:15]
	ds_read_b64_tr_b16 v[92:93], v186 offset:53888
	ds_read_b64_tr_b16 v[94:95], v186 offset:58368
	s_nop 11
	v_pk_mul_f32 v[0:1], v[0:1], v[44:45] op_sel_hi:[1,0]
	v_pk_mul_f32 v[2:3], v[2:3], v[44:45] op_sel_hi:[1,0]
	v_pk_mul_f32 v[4:5], v[4:5], v[44:45] op_sel_hi:[1,0]
	v_pk_mul_f32 v[6:7], v[6:7], v[44:45] op_sel_hi:[1,0]
	v_cvt_pk_bf16_f32 v0, v0, v1
	v_cvt_pk_bf16_f32 v1, v2, v3
	v_cvt_pk_bf16_f32 v2, v4, v5
	v_cvt_pk_bf16_f32 v3, v6, v7
	s_nop 1
	v_permlane32_swap_b32_e32 v0, v2
	v_permlane32_swap_b32_e32 v1, v3
	global_store_dwordx4 v[124:125], v[0:3], off offset:64
	v_pk_mul_f32 v[8:9], v[8:9], v[44:45] op_sel_hi:[1,0]
	v_pk_mul_f32 v[10:11], v[10:11], v[44:45] op_sel_hi:[1,0]
	v_pk_mul_f32 v[12:13], v[12:13], v[44:45] op_sel_hi:[1,0]
	v_pk_mul_f32 v[14:15], v[14:15], v[44:45] op_sel_hi:[1,0]
	v_cvt_pk_bf16_f32 v4, v8, v9
	v_cvt_pk_bf16_f32 v5, v10, v11
	v_cvt_pk_bf16_f32 v6, v12, v13
	v_cvt_pk_bf16_f32 v7, v14, v15
	s_nop 1
	v_permlane32_swap_b32_e32 v4, v6
	v_permlane32_swap_b32_e32 v5, v7
	global_store_dwordx4 v[124:125], v[4:7], off offset:96
	s_nop 1
	s_waitcnt lgkmcnt(12)
	v_mfma_f32_32x32x16_bf16 v[0:15], v[104:107], v[116:119], 0
	v_add_u32_e32 v40, v187, v205
	ds_read_b64_tr_b16 v[104:105], v186 offset:62848
	ds_read_b64_tr_b16 v[106:107], v40
	s_waitcnt lgkmcnt(12)
	v_mfma_f32_32x32x16_bf16 v[0:15], v[108:111], v[112:115], v[0:15]
	v_add_u32_e32 v40, v188, v205
	v_add_u32_e32 v42, v189, v205
	ds_read_b64_tr_b16 v[108:109], v40
	ds_read_b64_tr_b16 v[110:111], v42
	s_waitcnt lgkmcnt(12)
	v_mfma_f32_32x32x16_bf16 v[0:15], v[120:123], v[100:103], v[0:15]
	v_add_u32_e32 v40, v190, v205
	v_add_u32_e32 v42, v191, v205
	ds_read_b64_tr_b16 v[120:121], v40
	ds_read_b64_tr_b16 v[122:123], v42
	s_waitcnt lgkmcnt(12)
	v_mfma_f32_32x32x16_bf16 v[0:15], v[56:59], v[96:99], v[0:15]
	v_add_u32_e32 v40, v192, v205
	v_add_u32_e32 v42, v193, v205
	ds_read_b64_tr_b16 v[56:57], v40
	ds_read_b64_tr_b16 v[58:59], v42
	s_waitcnt lgkmcnt(12)
	v_mfma_f32_32x32x16_bf16 v[0:15], v[60:63], v[84:87], v[0:15]
	v_add_u32_e32 v40, v194, v205
	v_add_u32_e32 v42, v195, v205
	ds_read_b64_tr_b16 v[60:61], v40
	ds_read_b64_tr_b16 v[62:63], v42
	s_waitcnt lgkmcnt(12)
	v_mfma_f32_32x32x16_bf16 v[0:15], v[88:91], v[80:83], v[0:15]
	v_add_u32_e32 v40, v196, v205
	v_add_u32_e32 v42, v197, v205
	ds_read_b64_tr_b16 v[88:89], v40
	ds_read_b64_tr_b16 v[90:91], v42
	s_waitcnt lgkmcnt(12)
	v_mfma_f32_32x32x16_bf16 v[0:15], v[92:95], v[68:71], v[0:15]
	v_add_u32_e32 v40, v198, v205
	v_add_u32_e32 v42, v199, v205
	ds_read_b64_tr_b16 v[92:93], v40
	ds_read_b64_tr_b16 v[94:95], v42
	s_waitcnt lgkmcnt(12)
	v_mfma_f32_32x32x16_bf16 v[0:15], v[104:107], v[64:67], v[0:15]
	v_add_u32_e32 v40, v200, v205
	v_add_u32_e32 v42, v201, v205
	ds_read_b64_tr_b16 v[104:105], v40
	ds_read_b64_tr_b16 v[106:107], v42
	s_waitcnt lgkmcnt(12)
	v_mfma_f32_32x32x16_bf16 v[0:15], v[108:111], v[52:55], v[0:15]
	v_add_u32_e32 v40, v202, v205
	v_add_u32_e32 v42, v203, v205
	ds_read_b64_tr_b16 v[108:109], v40
	ds_read_b64_tr_b16 v[110:111], v42
	s_waitcnt lgkmcnt(12)
	v_mfma_f32_32x32x16_bf16 v[0:15], v[120:123], v[48:51], v[0:15]
	ds_read_b64_tr_b16 v[120:121], v186 offset:192
	ds_read_b64_tr_b16 v[122:123], v186 offset:4672
	s_waitcnt lgkmcnt(12)
	v_mfma_f32_32x32x16_bf16 v[0:15], v[56:59], v[36:39], v[0:15]
	ds_read_b64_tr_b16 v[56:57], v186 offset:9152
	ds_read_b64_tr_b16 v[58:59], v186 offset:13632
	s_waitcnt lgkmcnt(12)
	v_mfma_f32_32x32x16_bf16 v[0:15], v[60:63], v[32:35], v[0:15]
	ds_read_b64_tr_b16 v[60:61], v186 offset:18112
	ds_read_b64_tr_b16 v[62:63], v186 offset:22592
	s_waitcnt lgkmcnt(12)
	v_mfma_f32_32x32x16_bf16 v[0:15], v[88:91], v[20:23], v[0:15]
	ds_read_b64_tr_b16 v[88:89], v186 offset:27072
	ds_read_b64_tr_b16 v[90:91], v186 offset:31552
	s_waitcnt lgkmcnt(12)
	v_mfma_f32_32x32x16_bf16 v[0:15], v[92:95], v[16:19], v[0:15]
	ds_read_b64_tr_b16 v[92:93], v186 offset:36032
	ds_read_b64_tr_b16 v[94:95], v186 offset:40512
	s_waitcnt lgkmcnt(12)
	v_mfma_f32_32x32x16_bf16 v[0:15], v[104:107], v[28:31], v[0:15]
	ds_read_b64_tr_b16 v[104:105], v186 offset:44992
	ds_read_b64_tr_b16 v[106:107], v186 offset:49472
	s_waitcnt lgkmcnt(12)
	v_mfma_f32_32x32x16_bf16 v[0:15], v[108:111], v[24:27], v[0:15]
	ds_read_b64_tr_b16 v[108:109], v186 offset:53952
	ds_read_b64_tr_b16 v[110:111], v186 offset:58432
	s_nop 11
	v_pk_mul_f32 v[0:1], v[0:1], v[44:45] op_sel_hi:[1,0]
	v_pk_mul_f32 v[2:3], v[2:3], v[44:45] op_sel_hi:[1,0]
	v_pk_mul_f32 v[4:5], v[4:5], v[44:45] op_sel_hi:[1,0]
	v_pk_mul_f32 v[6:7], v[6:7], v[44:45] op_sel_hi:[1,0]
	v_cvt_pk_bf16_f32 v0, v0, v1
	v_cvt_pk_bf16_f32 v1, v2, v3
	v_cvt_pk_bf16_f32 v2, v4, v5
	v_cvt_pk_bf16_f32 v3, v6, v7
	s_nop 1
	v_permlane32_swap_b32_e32 v0, v2
	v_permlane32_swap_b32_e32 v1, v3
	global_store_dwordx4 v[124:125], v[0:3], off offset:128
	v_pk_mul_f32 v[8:9], v[8:9], v[44:45] op_sel_hi:[1,0]
	v_pk_mul_f32 v[10:11], v[10:11], v[44:45] op_sel_hi:[1,0]
	v_pk_mul_f32 v[12:13], v[12:13], v[44:45] op_sel_hi:[1,0]
	v_pk_mul_f32 v[14:15], v[14:15], v[44:45] op_sel_hi:[1,0]
	v_cvt_pk_bf16_f32 v4, v8, v9
	v_cvt_pk_bf16_f32 v5, v10, v11
	v_cvt_pk_bf16_f32 v6, v12, v13
	v_cvt_pk_bf16_f32 v7, v14, v15
	s_nop 1
	v_permlane32_swap_b32_e32 v4, v6
	v_permlane32_swap_b32_e32 v5, v7
	global_store_dwordx4 v[124:125], v[4:7], off offset:160
	s_nop 1
	s_waitcnt lgkmcnt(12)
	v_mfma_f32_32x32x16_bf16 v[0:15], v[120:123], v[116:119], 0
	v_add_u32_e32 v40, v187, v206
	ds_read_b64_tr_b16 v[120:121], v186 offset:62912
	ds_read_b64_tr_b16 v[122:123], v40
	s_waitcnt lgkmcnt(12)
	v_mfma_f32_32x32x16_bf16 v[0:15], v[56:59], v[112:115], v[0:15]
	v_add_u32_e32 v40, v188, v206
	v_add_u32_e32 v42, v189, v206
	ds_read_b64_tr_b16 v[56:57], v40
	ds_read_b64_tr_b16 v[58:59], v42
	s_waitcnt lgkmcnt(12)
	v_mfma_f32_32x32x16_bf16 v[0:15], v[60:63], v[100:103], v[0:15]
	v_add_u32_e32 v40, v190, v206
	v_add_u32_e32 v42, v191, v206
	ds_read_b64_tr_b16 v[60:61], v40
	ds_read_b64_tr_b16 v[62:63], v42
	s_waitcnt lgkmcnt(12)
	v_mfma_f32_32x32x16_bf16 v[0:15], v[88:91], v[96:99], v[0:15]
	v_add_u32_e32 v40, v192, v206
	v_add_u32_e32 v42, v193, v206
	ds_read_b64_tr_b16 v[88:89], v40
	ds_read_b64_tr_b16 v[90:91], v42
	s_waitcnt lgkmcnt(12)
	v_mfma_f32_32x32x16_bf16 v[0:15], v[92:95], v[84:87], v[0:15]
	v_add_u32_e32 v40, v194, v206
	v_add_u32_e32 v42, v195, v206
	ds_read_b64_tr_b16 v[92:93], v40
	ds_read_b64_tr_b16 v[94:95], v42
	s_waitcnt lgkmcnt(12)
	v_mfma_f32_32x32x16_bf16 v[0:15], v[104:107], v[80:83], v[0:15]
	v_add_u32_e32 v40, v196, v206
	v_add_u32_e32 v42, v197, v206
	ds_read_b64_tr_b16 v[104:105], v40
	ds_read_b64_tr_b16 v[106:107], v42
	s_waitcnt lgkmcnt(12)
	v_mfma_f32_32x32x16_bf16 v[0:15], v[108:111], v[68:71], v[0:15]
	v_add_u32_e32 v40, v198, v206
	v_add_u32_e32 v42, v199, v206
	ds_read_b64_tr_b16 v[108:109], v40
	ds_read_b64_tr_b16 v[110:111], v42
	s_waitcnt lgkmcnt(12)
	v_mfma_f32_32x32x16_bf16 v[0:15], v[120:123], v[64:67], v[0:15]
	v_add_u32_e32 v40, v200, v206
	v_add_u32_e32 v42, v201, v206
	ds_read_b64_tr_b16 v[120:121], v40
	ds_read_b64_tr_b16 v[122:123], v42
	s_waitcnt lgkmcnt(12)
	v_mfma_f32_32x32x16_bf16 v[0:15], v[56:59], v[52:55], v[0:15]
	v_add_u32_e32 v40, v202, v206
	v_add_u32_e32 v42, v203, v206
	ds_read_b64_tr_b16 v[56:57], v40
	ds_read_b64_tr_b16 v[58:59], v42
	s_waitcnt lgkmcnt(12)
	v_mfma_f32_32x32x16_bf16 v[0:15], v[60:63], v[48:51], v[0:15]
	ds_read_b64_tr_b16 v[60:61], v186 offset:256
	ds_read_b64_tr_b16 v[62:63], v186 offset:4736
	s_waitcnt lgkmcnt(12)
	v_mfma_f32_32x32x16_bf16 v[0:15], v[88:91], v[36:39], v[0:15]
	ds_read_b64_tr_b16 v[88:89], v186 offset:9216
	ds_read_b64_tr_b16 v[90:91], v186 offset:13696
	s_waitcnt lgkmcnt(12)
	v_mfma_f32_32x32x16_bf16 v[0:15], v[92:95], v[32:35], v[0:15]
	ds_read_b64_tr_b16 v[92:93], v186 offset:18176
	ds_read_b64_tr_b16 v[94:95], v186 offset:22656
	s_waitcnt lgkmcnt(12)
	v_mfma_f32_32x32x16_bf16 v[0:15], v[104:107], v[20:23], v[0:15]
	ds_read_b64_tr_b16 v[104:105], v186 offset:27136
	ds_read_b64_tr_b16 v[106:107], v186 offset:31616
	s_waitcnt lgkmcnt(12)
	v_mfma_f32_32x32x16_bf16 v[0:15], v[108:111], v[16:19], v[0:15]
	ds_read_b64_tr_b16 v[108:109], v186 offset:36096
	ds_read_b64_tr_b16 v[110:111], v186 offset:40576
	s_waitcnt lgkmcnt(12)
	v_mfma_f32_32x32x16_bf16 v[0:15], v[120:123], v[28:31], v[0:15]
	ds_read_b64_tr_b16 v[120:121], v186 offset:45056
	ds_read_b64_tr_b16 v[122:123], v186 offset:49536
	s_waitcnt lgkmcnt(12)
	v_mfma_f32_32x32x16_bf16 v[0:15], v[56:59], v[24:27], v[0:15]
	ds_read_b64_tr_b16 v[56:57], v186 offset:54016
	ds_read_b64_tr_b16 v[58:59], v186 offset:58496
	s_nop 11
	v_pk_mul_f32 v[0:1], v[0:1], v[44:45] op_sel_hi:[1,0]
	v_pk_mul_f32 v[2:3], v[2:3], v[44:45] op_sel_hi:[1,0]
	v_pk_mul_f32 v[4:5], v[4:5], v[44:45] op_sel_hi:[1,0]
	v_pk_mul_f32 v[6:7], v[6:7], v[44:45] op_sel_hi:[1,0]
	v_cvt_pk_bf16_f32 v0, v0, v1
	v_cvt_pk_bf16_f32 v1, v2, v3
	v_cvt_pk_bf16_f32 v2, v4, v5
	v_cvt_pk_bf16_f32 v3, v6, v7
	s_nop 1
	v_permlane32_swap_b32_e32 v0, v2
	v_permlane32_swap_b32_e32 v1, v3
	global_store_dwordx4 v[124:125], v[0:3], off offset:192
	v_pk_mul_f32 v[8:9], v[8:9], v[44:45] op_sel_hi:[1,0]
	v_pk_mul_f32 v[10:11], v[10:11], v[44:45] op_sel_hi:[1,0]
	v_pk_mul_f32 v[12:13], v[12:13], v[44:45] op_sel_hi:[1,0]
	v_pk_mul_f32 v[14:15], v[14:15], v[44:45] op_sel_hi:[1,0]
	v_cvt_pk_bf16_f32 v4, v8, v9
	v_cvt_pk_bf16_f32 v5, v10, v11
	v_cvt_pk_bf16_f32 v6, v12, v13
	v_cvt_pk_bf16_f32 v7, v14, v15
	s_nop 1
	v_permlane32_swap_b32_e32 v4, v6
	v_permlane32_swap_b32_e32 v5, v7
	global_store_dwordx4 v[124:125], v[4:7], off offset:224
	s_nop 1
	s_waitcnt lgkmcnt(12)
	v_mfma_f32_32x32x16_bf16 v[0:15], v[60:63], v[116:119], 0
	v_add_u32_e32 v40, v187, v207
	ds_read_b64_tr_b16 v[60:61], v186 offset:62976
	ds_read_b64_tr_b16 v[62:63], v40
	s_waitcnt lgkmcnt(12)
	v_mfma_f32_32x32x16_bf16 v[0:15], v[88:91], v[112:115], v[0:15]
	v_add_u32_e32 v40, v188, v207
	v_add_u32_e32 v42, v189, v207
	ds_read_b64_tr_b16 v[88:89], v40
	ds_read_b64_tr_b16 v[90:91], v42
	s_waitcnt lgkmcnt(12)
	v_mfma_f32_32x32x16_bf16 v[0:15], v[92:95], v[100:103], v[0:15]
	v_add_u32_e32 v40, v190, v207
	v_add_u32_e32 v42, v191, v207
	ds_read_b64_tr_b16 v[92:93], v40
	ds_read_b64_tr_b16 v[94:95], v42
	s_waitcnt lgkmcnt(12)
	v_mfma_f32_32x32x16_bf16 v[0:15], v[104:107], v[96:99], v[0:15]
	v_add_u32_e32 v40, v192, v207
	v_add_u32_e32 v42, v193, v207
	ds_read_b64_tr_b16 v[104:105], v40
	ds_read_b64_tr_b16 v[106:107], v42
	s_waitcnt lgkmcnt(12)
	v_mfma_f32_32x32x16_bf16 v[0:15], v[108:111], v[84:87], v[0:15]
	v_add_u32_e32 v40, v194, v207
	v_add_u32_e32 v42, v195, v207
	ds_read_b64_tr_b16 v[108:109], v40
	ds_read_b64_tr_b16 v[110:111], v42
	s_waitcnt lgkmcnt(12)
	v_mfma_f32_32x32x16_bf16 v[0:15], v[120:123], v[80:83], v[0:15]
	v_add_u32_e32 v40, v196, v207
	v_add_u32_e32 v42, v197, v207
	ds_read_b64_tr_b16 v[120:121], v40
	ds_read_b64_tr_b16 v[122:123], v42
	s_waitcnt lgkmcnt(12)
	v_mfma_f32_32x32x16_bf16 v[0:15], v[56:59], v[68:71], v[0:15]
	v_add_u32_e32 v40, v198, v207
	v_add_u32_e32 v42, v199, v207
	ds_read_b64_tr_b16 v[56:57], v40
	ds_read_b64_tr_b16 v[58:59], v42
	s_waitcnt lgkmcnt(12)
	v_mfma_f32_32x32x16_bf16 v[0:15], v[60:63], v[64:67], v[0:15]
	v_add_u32_e32 v40, v200, v207
	v_add_u32_e32 v42, v201, v207
	ds_read_b64_tr_b16 v[60:61], v40
	ds_read_b64_tr_b16 v[62:63], v42
	s_waitcnt lgkmcnt(12)
	v_mfma_f32_32x32x16_bf16 v[0:15], v[88:91], v[52:55], v[0:15]
	v_add_u32_e32 v40, v202, v207
	v_add_u32_e32 v42, v203, v207
	ds_read_b64_tr_b16 v[88:89], v40
	ds_read_b64_tr_b16 v[90:91], v42
	s_waitcnt lgkmcnt(12)
	v_mfma_f32_32x32x16_bf16 v[0:15], v[92:95], v[48:51], v[0:15]
	ds_read_b64_tr_b16 v[92:93], v186 offset:320
	ds_read_b64_tr_b16 v[94:95], v186 offset:4800
	s_waitcnt lgkmcnt(12)
	v_mfma_f32_32x32x16_bf16 v[0:15], v[104:107], v[36:39], v[0:15]
	ds_read_b64_tr_b16 v[104:105], v186 offset:9280
	ds_read_b64_tr_b16 v[106:107], v186 offset:13760
	s_waitcnt lgkmcnt(12)
	v_mfma_f32_32x32x16_bf16 v[0:15], v[108:111], v[32:35], v[0:15]
	ds_read_b64_tr_b16 v[108:109], v186 offset:18240
	ds_read_b64_tr_b16 v[110:111], v186 offset:22720
	s_waitcnt lgkmcnt(12)
	v_mfma_f32_32x32x16_bf16 v[0:15], v[120:123], v[20:23], v[0:15]
	ds_read_b64_tr_b16 v[120:121], v186 offset:27200
	ds_read_b64_tr_b16 v[122:123], v186 offset:31680
	s_waitcnt lgkmcnt(12)
	v_mfma_f32_32x32x16_bf16 v[0:15], v[56:59], v[16:19], v[0:15]
	ds_read_b64_tr_b16 v[56:57], v186 offset:36160
	ds_read_b64_tr_b16 v[58:59], v186 offset:40640
	s_waitcnt lgkmcnt(12)
	v_mfma_f32_32x32x16_bf16 v[0:15], v[60:63], v[28:31], v[0:15]
	ds_read_b64_tr_b16 v[60:61], v186 offset:45120
	ds_read_b64_tr_b16 v[62:63], v186 offset:49600
	s_waitcnt lgkmcnt(12)
	v_mfma_f32_32x32x16_bf16 v[0:15], v[88:91], v[24:27], v[0:15]
	ds_read_b64_tr_b16 v[88:89], v186 offset:54080
	ds_read_b64_tr_b16 v[90:91], v186 offset:58560
	s_nop 11
	v_pk_mul_f32 v[0:1], v[0:1], v[44:45] op_sel_hi:[1,0]
	v_pk_mul_f32 v[2:3], v[2:3], v[44:45] op_sel_hi:[1,0]
	v_pk_mul_f32 v[4:5], v[4:5], v[44:45] op_sel_hi:[1,0]
	v_pk_mul_f32 v[6:7], v[6:7], v[44:45] op_sel_hi:[1,0]
	v_cvt_pk_bf16_f32 v0, v0, v1
	v_cvt_pk_bf16_f32 v1, v2, v3
	v_cvt_pk_bf16_f32 v2, v4, v5
	v_cvt_pk_bf16_f32 v3, v6, v7
	s_nop 1
	v_permlane32_swap_b32_e32 v0, v2
	v_permlane32_swap_b32_e32 v1, v3
	global_store_dwordx4 v[124:125], v[0:3], off offset:256
	v_pk_mul_f32 v[8:9], v[8:9], v[44:45] op_sel_hi:[1,0]
	v_pk_mul_f32 v[10:11], v[10:11], v[44:45] op_sel_hi:[1,0]
	v_pk_mul_f32 v[12:13], v[12:13], v[44:45] op_sel_hi:[1,0]
	v_pk_mul_f32 v[14:15], v[14:15], v[44:45] op_sel_hi:[1,0]
	v_cvt_pk_bf16_f32 v4, v8, v9
	v_cvt_pk_bf16_f32 v5, v10, v11
	v_cvt_pk_bf16_f32 v6, v12, v13
	v_cvt_pk_bf16_f32 v7, v14, v15
	s_nop 1
	v_permlane32_swap_b32_e32 v4, v6
	v_permlane32_swap_b32_e32 v5, v7
	global_store_dwordx4 v[124:125], v[4:7], off offset:288
	s_nop 1
	s_waitcnt lgkmcnt(12)
	v_mfma_f32_32x32x16_bf16 v[0:15], v[92:95], v[116:119], 0
	v_add_u32_e32 v40, v187, v208
	ds_read_b64_tr_b16 v[92:93], v186 offset:63040
	ds_read_b64_tr_b16 v[94:95], v40
	s_waitcnt lgkmcnt(12)
	v_mfma_f32_32x32x16_bf16 v[0:15], v[104:107], v[112:115], v[0:15]
	v_add_u32_e32 v40, v188, v208
	v_add_u32_e32 v42, v189, v208
	ds_read_b64_tr_b16 v[104:105], v40
	ds_read_b64_tr_b16 v[106:107], v42
	s_waitcnt lgkmcnt(12)
	v_mfma_f32_32x32x16_bf16 v[0:15], v[108:111], v[100:103], v[0:15]
	v_add_u32_e32 v40, v190, v208
	v_add_u32_e32 v42, v191, v208
	ds_read_b64_tr_b16 v[108:109], v40
	ds_read_b64_tr_b16 v[110:111], v42
	s_waitcnt lgkmcnt(12)
	v_mfma_f32_32x32x16_bf16 v[0:15], v[120:123], v[96:99], v[0:15]
	v_add_u32_e32 v40, v192, v208
	v_add_u32_e32 v42, v193, v208
	ds_read_b64_tr_b16 v[120:121], v40
	ds_read_b64_tr_b16 v[122:123], v42
	s_waitcnt lgkmcnt(12)
	v_mfma_f32_32x32x16_bf16 v[0:15], v[56:59], v[84:87], v[0:15]
	v_add_u32_e32 v40, v194, v208
	v_add_u32_e32 v42, v195, v208
	ds_read_b64_tr_b16 v[56:57], v40
	ds_read_b64_tr_b16 v[58:59], v42
	s_waitcnt lgkmcnt(12)
	v_mfma_f32_32x32x16_bf16 v[0:15], v[60:63], v[80:83], v[0:15]
	v_add_u32_e32 v40, v196, v208
	v_add_u32_e32 v42, v197, v208
	ds_read_b64_tr_b16 v[60:61], v40
	ds_read_b64_tr_b16 v[62:63], v42
	s_waitcnt lgkmcnt(12)
	v_mfma_f32_32x32x16_bf16 v[0:15], v[88:91], v[68:71], v[0:15]
	v_add_u32_e32 v40, v198, v208
	v_add_u32_e32 v42, v199, v208
	ds_read_b64_tr_b16 v[88:89], v40
	ds_read_b64_tr_b16 v[90:91], v42
	s_waitcnt lgkmcnt(12)
	v_mfma_f32_32x32x16_bf16 v[0:15], v[92:95], v[64:67], v[0:15]
	v_add_u32_e32 v40, v200, v208
	v_add_u32_e32 v42, v201, v208
	ds_read_b64_tr_b16 v[92:93], v40
	ds_read_b64_tr_b16 v[94:95], v42
	s_waitcnt lgkmcnt(12)
	v_mfma_f32_32x32x16_bf16 v[0:15], v[104:107], v[52:55], v[0:15]
	v_add_u32_e32 v40, v202, v208
	v_add_u32_e32 v42, v203, v208
	ds_read_b64_tr_b16 v[104:105], v40
	ds_read_b64_tr_b16 v[106:107], v42
	s_waitcnt lgkmcnt(12)
	v_mfma_f32_32x32x16_bf16 v[0:15], v[108:111], v[48:51], v[0:15]
	ds_read_b64_tr_b16 v[108:109], v186 offset:384
	ds_read_b64_tr_b16 v[110:111], v186 offset:4864
	s_waitcnt lgkmcnt(12)
	v_mfma_f32_32x32x16_bf16 v[0:15], v[120:123], v[36:39], v[0:15]
	ds_read_b64_tr_b16 v[120:121], v186 offset:9344
	ds_read_b64_tr_b16 v[122:123], v186 offset:13824
	s_waitcnt lgkmcnt(12)
	v_mfma_f32_32x32x16_bf16 v[0:15], v[56:59], v[32:35], v[0:15]
	ds_read_b64_tr_b16 v[56:57], v186 offset:18304
	ds_read_b64_tr_b16 v[58:59], v186 offset:22784
	s_waitcnt lgkmcnt(12)
	v_mfma_f32_32x32x16_bf16 v[0:15], v[60:63], v[20:23], v[0:15]
	ds_read_b64_tr_b16 v[60:61], v186 offset:27264
	ds_read_b64_tr_b16 v[62:63], v186 offset:31744
	s_waitcnt lgkmcnt(12)
	v_mfma_f32_32x32x16_bf16 v[0:15], v[88:91], v[16:19], v[0:15]
	ds_read_b64_tr_b16 v[88:89], v186 offset:36224
	ds_read_b64_tr_b16 v[90:91], v186 offset:40704
	s_waitcnt lgkmcnt(12)
	v_mfma_f32_32x32x16_bf16 v[0:15], v[92:95], v[28:31], v[0:15]
	ds_read_b64_tr_b16 v[92:93], v186 offset:45184
	ds_read_b64_tr_b16 v[94:95], v186 offset:49664
	s_waitcnt lgkmcnt(12)
	v_mfma_f32_32x32x16_bf16 v[0:15], v[104:107], v[24:27], v[0:15]
	ds_read_b64_tr_b16 v[104:105], v186 offset:54144
	ds_read_b64_tr_b16 v[106:107], v186 offset:58624
	s_nop 11
	v_pk_mul_f32 v[0:1], v[0:1], v[44:45] op_sel_hi:[1,0]
	v_pk_mul_f32 v[2:3], v[2:3], v[44:45] op_sel_hi:[1,0]
	v_pk_mul_f32 v[4:5], v[4:5], v[44:45] op_sel_hi:[1,0]
	v_pk_mul_f32 v[6:7], v[6:7], v[44:45] op_sel_hi:[1,0]
	v_cvt_pk_bf16_f32 v0, v0, v1
	v_cvt_pk_bf16_f32 v1, v2, v3
	v_cvt_pk_bf16_f32 v2, v4, v5
	v_cvt_pk_bf16_f32 v3, v6, v7
	s_nop 1
	v_permlane32_swap_b32_e32 v0, v2
	v_permlane32_swap_b32_e32 v1, v3
	global_store_dwordx4 v[124:125], v[0:3], off offset:320
	v_pk_mul_f32 v[8:9], v[8:9], v[44:45] op_sel_hi:[1,0]
	v_pk_mul_f32 v[10:11], v[10:11], v[44:45] op_sel_hi:[1,0]
	v_pk_mul_f32 v[12:13], v[12:13], v[44:45] op_sel_hi:[1,0]
	v_pk_mul_f32 v[14:15], v[14:15], v[44:45] op_sel_hi:[1,0]
	v_cvt_pk_bf16_f32 v4, v8, v9
	v_cvt_pk_bf16_f32 v5, v10, v11
	v_cvt_pk_bf16_f32 v6, v12, v13
	v_cvt_pk_bf16_f32 v7, v14, v15
	s_nop 1
	v_permlane32_swap_b32_e32 v4, v6
	v_permlane32_swap_b32_e32 v5, v7
	global_store_dwordx4 v[124:125], v[4:7], off offset:352
	s_nop 1
	s_waitcnt lgkmcnt(12)
	v_mfma_f32_32x32x16_bf16 v[0:15], v[108:111], v[116:119], 0
	v_add_u32_e32 v40, v187, v209
	ds_read_b64_tr_b16 v[108:109], v186 offset:63104
	ds_read_b64_tr_b16 v[110:111], v40
	s_waitcnt lgkmcnt(12)
	v_mfma_f32_32x32x16_bf16 v[0:15], v[120:123], v[112:115], v[0:15]
	v_add_u32_e32 v40, v188, v209
	v_add_u32_e32 v42, v189, v209
	ds_read_b64_tr_b16 v[120:121], v40
	ds_read_b64_tr_b16 v[122:123], v42
	s_waitcnt lgkmcnt(12)
	v_mfma_f32_32x32x16_bf16 v[0:15], v[56:59], v[100:103], v[0:15]
	v_add_u32_e32 v40, v190, v209
	v_add_u32_e32 v42, v191, v209
	ds_read_b64_tr_b16 v[56:57], v40
	ds_read_b64_tr_b16 v[58:59], v42
	s_waitcnt lgkmcnt(12)
	v_mfma_f32_32x32x16_bf16 v[0:15], v[60:63], v[96:99], v[0:15]
	v_add_u32_e32 v40, v192, v209
	v_add_u32_e32 v42, v193, v209
	ds_read_b64_tr_b16 v[60:61], v40
	ds_read_b64_tr_b16 v[62:63], v42
	s_waitcnt lgkmcnt(12)
	v_mfma_f32_32x32x16_bf16 v[0:15], v[88:91], v[84:87], v[0:15]
	v_add_u32_e32 v40, v194, v209
	v_add_u32_e32 v42, v195, v209
	ds_read_b64_tr_b16 v[88:89], v40
	ds_read_b64_tr_b16 v[90:91], v42
	s_waitcnt lgkmcnt(12)
	v_mfma_f32_32x32x16_bf16 v[0:15], v[92:95], v[80:83], v[0:15]
	v_add_u32_e32 v40, v196, v209
	v_add_u32_e32 v42, v197, v209
	ds_read_b64_tr_b16 v[92:93], v40
	ds_read_b64_tr_b16 v[94:95], v42
	s_waitcnt lgkmcnt(12)
	v_mfma_f32_32x32x16_bf16 v[0:15], v[104:107], v[68:71], v[0:15]
	v_add_u32_e32 v40, v198, v209
	v_add_u32_e32 v42, v199, v209
	ds_read_b64_tr_b16 v[104:105], v40
	ds_read_b64_tr_b16 v[106:107], v42
	s_waitcnt lgkmcnt(12)
	v_mfma_f32_32x32x16_bf16 v[0:15], v[108:111], v[64:67], v[0:15]
	v_add_u32_e32 v40, v200, v209
	v_add_u32_e32 v42, v201, v209
	ds_read_b64_tr_b16 v[108:109], v40
	ds_read_b64_tr_b16 v[110:111], v42
	s_waitcnt lgkmcnt(12)
	v_mfma_f32_32x32x16_bf16 v[0:15], v[120:123], v[52:55], v[0:15]
	v_add_u32_e32 v40, v202, v209
	v_add_u32_e32 v42, v203, v209
	ds_read_b64_tr_b16 v[120:121], v40
	ds_read_b64_tr_b16 v[122:123], v42
	s_waitcnt lgkmcnt(12)
	v_mfma_f32_32x32x16_bf16 v[0:15], v[56:59], v[48:51], v[0:15]
	ds_read_b64_tr_b16 v[56:57], v186 offset:448
	ds_read_b64_tr_b16 v[58:59], v186 offset:4928
	s_waitcnt lgkmcnt(12)
	v_mfma_f32_32x32x16_bf16 v[0:15], v[60:63], v[36:39], v[0:15]
	ds_read_b64_tr_b16 v[60:61], v186 offset:9408
	ds_read_b64_tr_b16 v[62:63], v186 offset:13888
	s_waitcnt lgkmcnt(12)
	v_mfma_f32_32x32x16_bf16 v[0:15], v[88:91], v[32:35], v[0:15]
	ds_read_b64_tr_b16 v[88:89], v186 offset:18368
	ds_read_b64_tr_b16 v[90:91], v186 offset:22848
	s_waitcnt lgkmcnt(12)
	v_mfma_f32_32x32x16_bf16 v[0:15], v[92:95], v[20:23], v[0:15]
	ds_read_b64_tr_b16 v[92:93], v186 offset:27328
	ds_read_b64_tr_b16 v[94:95], v186 offset:31808
	s_waitcnt lgkmcnt(12)
	v_mfma_f32_32x32x16_bf16 v[0:15], v[104:107], v[16:19], v[0:15]
	ds_read_b64_tr_b16 v[104:105], v186 offset:36288
	ds_read_b64_tr_b16 v[106:107], v186 offset:40768
	s_waitcnt lgkmcnt(12)
	v_mfma_f32_32x32x16_bf16 v[0:15], v[108:111], v[28:31], v[0:15]
	ds_read_b64_tr_b16 v[108:109], v186 offset:45248
	ds_read_b64_tr_b16 v[110:111], v186 offset:49728
	s_waitcnt lgkmcnt(12)
	v_mfma_f32_32x32x16_bf16 v[0:15], v[120:123], v[24:27], v[0:15]
	ds_read_b64_tr_b16 v[120:121], v186 offset:54208
	ds_read_b64_tr_b16 v[122:123], v186 offset:58688
	s_nop 11
	v_pk_mul_f32 v[0:1], v[0:1], v[44:45] op_sel_hi:[1,0]
	v_pk_mul_f32 v[2:3], v[2:3], v[44:45] op_sel_hi:[1,0]
	v_pk_mul_f32 v[4:5], v[4:5], v[44:45] op_sel_hi:[1,0]
	v_pk_mul_f32 v[6:7], v[6:7], v[44:45] op_sel_hi:[1,0]
	v_cvt_pk_bf16_f32 v0, v0, v1
	v_cvt_pk_bf16_f32 v1, v2, v3
	v_cvt_pk_bf16_f32 v2, v4, v5
	v_cvt_pk_bf16_f32 v3, v6, v7
	s_nop 1
	v_permlane32_swap_b32_e32 v0, v2
	v_permlane32_swap_b32_e32 v1, v3
	global_store_dwordx4 v[124:125], v[0:3], off offset:384
	v_pk_mul_f32 v[8:9], v[8:9], v[44:45] op_sel_hi:[1,0]
	v_pk_mul_f32 v[10:11], v[10:11], v[44:45] op_sel_hi:[1,0]
	v_pk_mul_f32 v[12:13], v[12:13], v[44:45] op_sel_hi:[1,0]
	v_pk_mul_f32 v[14:15], v[14:15], v[44:45] op_sel_hi:[1,0]
	v_cvt_pk_bf16_f32 v4, v8, v9
	v_cvt_pk_bf16_f32 v5, v10, v11
	v_cvt_pk_bf16_f32 v6, v12, v13
	v_cvt_pk_bf16_f32 v7, v14, v15
	s_nop 1
	v_permlane32_swap_b32_e32 v4, v6
	v_permlane32_swap_b32_e32 v5, v7
	global_store_dwordx4 v[124:125], v[4:7], off offset:416
	s_nop 1
	s_waitcnt lgkmcnt(12)
	v_mfma_f32_32x32x16_bf16 v[0:15], v[56:59], v[116:119], 0
	v_add_u32_e32 v40, v187, v210
	ds_read_b64_tr_b16 v[56:57], v186 offset:63168
	ds_read_b64_tr_b16 v[58:59], v40
	s_waitcnt lgkmcnt(12)
	v_mfma_f32_32x32x16_bf16 v[0:15], v[60:63], v[112:115], v[0:15]
	v_add_u32_e32 v40, v188, v210
	v_add_u32_e32 v42, v189, v210
	ds_read_b64_tr_b16 v[60:61], v40
	ds_read_b64_tr_b16 v[62:63], v42
	s_waitcnt lgkmcnt(12)
	v_mfma_f32_32x32x16_bf16 v[0:15], v[88:91], v[100:103], v[0:15]
	v_add_u32_e32 v40, v190, v210
	v_add_u32_e32 v42, v191, v210
	ds_read_b64_tr_b16 v[88:89], v40
	ds_read_b64_tr_b16 v[90:91], v42
	s_waitcnt lgkmcnt(12)
	v_mfma_f32_32x32x16_bf16 v[0:15], v[92:95], v[96:99], v[0:15]
	v_add_u32_e32 v40, v192, v210
	v_add_u32_e32 v42, v193, v210
	ds_read_b64_tr_b16 v[92:93], v40
	ds_read_b64_tr_b16 v[94:95], v42
	s_waitcnt lgkmcnt(12)
	v_mfma_f32_32x32x16_bf16 v[0:15], v[104:107], v[84:87], v[0:15]
	v_add_u32_e32 v40, v194, v210
	v_add_u32_e32 v42, v195, v210
	ds_read_b64_tr_b16 v[104:105], v40
	ds_read_b64_tr_b16 v[106:107], v42
	s_waitcnt lgkmcnt(12)
	v_mfma_f32_32x32x16_bf16 v[0:15], v[108:111], v[80:83], v[0:15]
	v_add_u32_e32 v40, v196, v210
	v_add_u32_e32 v42, v197, v210
	ds_read_b64_tr_b16 v[108:109], v40
	ds_read_b64_tr_b16 v[110:111], v42
	s_waitcnt lgkmcnt(12)
	v_mfma_f32_32x32x16_bf16 v[0:15], v[120:123], v[68:71], v[0:15]
	v_add_u32_e32 v40, v198, v210
	v_add_u32_e32 v42, v199, v210
	ds_read_b64_tr_b16 v[120:121], v40
	ds_read_b64_tr_b16 v[122:123], v42
	s_waitcnt lgkmcnt(12)
	v_mfma_f32_32x32x16_bf16 v[0:15], v[56:59], v[64:67], v[0:15]
	v_add_u32_e32 v40, v200, v210
	v_add_u32_e32 v42, v201, v210
	ds_read_b64_tr_b16 v[56:57], v40
	ds_read_b64_tr_b16 v[58:59], v42
	s_waitcnt lgkmcnt(12)
	v_mfma_f32_32x32x16_bf16 v[0:15], v[60:63], v[52:55], v[0:15]
	v_add_u32_e32 v40, v202, v210
	v_add_u32_e32 v42, v203, v210
	ds_read_b64_tr_b16 v[60:61], v40
	ds_read_b64_tr_b16 v[62:63], v42
	s_waitcnt lgkmcnt(12)
	v_mfma_f32_32x32x16_bf16 v[0:15], v[88:91], v[48:51], v[0:15]
	s_waitcnt lgkmcnt(10)
	v_mfma_f32_32x32x16_bf16 v[0:15], v[92:95], v[36:39], v[0:15]
	s_waitcnt lgkmcnt(8)
	v_mfma_f32_32x32x16_bf16 v[0:15], v[104:107], v[32:35], v[0:15]
	s_waitcnt lgkmcnt(6)
	v_mfma_f32_32x32x16_bf16 v[0:15], v[108:111], v[20:23], v[0:15]
	s_waitcnt lgkmcnt(4)
	v_mfma_f32_32x32x16_bf16 v[0:15], v[120:123], v[16:19], v[0:15]
	s_waitcnt lgkmcnt(2)
	v_mfma_f32_32x32x16_bf16 v[0:15], v[56:59], v[28:31], v[0:15]
	s_waitcnt lgkmcnt(0)
	v_mfma_f32_32x32x16_bf16 v[0:15], v[60:63], v[24:27], v[0:15]
	s_nop 11
	v_pk_mul_f32 v[0:1], v[0:1], v[44:45] op_sel_hi:[1,0]
	v_pk_mul_f32 v[2:3], v[2:3], v[44:45] op_sel_hi:[1,0]
	v_pk_mul_f32 v[4:5], v[4:5], v[44:45] op_sel_hi:[1,0]
	v_pk_mul_f32 v[6:7], v[6:7], v[44:45] op_sel_hi:[1,0]
	v_cvt_pk_bf16_f32 v0, v0, v1
	v_cvt_pk_bf16_f32 v1, v2, v3
	v_cvt_pk_bf16_f32 v2, v4, v5
	v_cvt_pk_bf16_f32 v3, v6, v7
	s_nop 1
	v_permlane32_swap_b32_e32 v0, v2
	v_permlane32_swap_b32_e32 v1, v3
	global_store_dwordx4 v[124:125], v[0:3], off offset:448
	v_pk_mul_f32 v[8:9], v[8:9], v[44:45] op_sel_hi:[1,0]
	v_pk_mul_f32 v[10:11], v[10:11], v[44:45] op_sel_hi:[1,0]
	v_pk_mul_f32 v[12:13], v[12:13], v[44:45] op_sel_hi:[1,0]
	v_pk_mul_f32 v[14:15], v[14:15], v[44:45] op_sel_hi:[1,0]
	v_cvt_pk_bf16_f32 v4, v8, v9
	v_cvt_pk_bf16_f32 v5, v10, v11
	v_cvt_pk_bf16_f32 v6, v12, v13
	v_cvt_pk_bf16_f32 v7, v14, v15
	s_nop 1
	v_permlane32_swap_b32_e32 v4, v6
	v_permlane32_swap_b32_e32 v5, v7
	global_store_dwordx4 v[124:125], v[4:7], off offset:480
	s_nop 1
	s_barrier
	s_branch .LBB0_751
